# stack: symmetric P1 loop with A/B half offset, epilogue z hoist, K swizzle, conv load hoist, P1 kind balancing
# speedup vs baseline: 1.0114x; 1.0012x over previous
; #define LAS __attribute__((address_space(3)))
;     __device__ bool next(int i, Unit& u) const {
;         const int ti = (NSEG == 2) ? (i >> 1) : i; u.seg = (NSEG == 2) ? (i & 1) : 0;
;         const long L = (long)ti * G + c; if (L >= nwg) return false;
;         int wgid = (int)L; { const int q = nwg / NXCD, r = nwg % NXCD, xcd = wgid % NXCD, off = wgid / NXCD; wgid = (xcd < r ? xcd * (q + 1) : r * (q + 1) + (xcd - r) * q) + off; }
;         const int nig = WGM * nN, gid = wgid / nig, fm = gid * WGM, gsz = (nM - fm) < WGM ? (nM - fm) : WGM;
;         u.pm = fm + ((wgid % nig) % gsz); u.pn = (wgid % nig) / gsz; return true;
;     }
; __global__ void __launch_bounds__(NTHREADS, 2) fox_fwd(Args args) {
;     ...
;         pg8::Gemm g{XN, WIN, nullptr, nullptr, MREAL, 20480, DM}; pg8::StaticOrder<1> S; S.init(MREAL, 20480, G, bx);
;         pg8::EpiProj E{Qb, Kb, Vb, Zb, P1b, P2b, Rb, S2b};
;         pg8::gemm_phase<pg8::EpiProj, pg8::StaticOrder<1>, 1>((LAS unsigned char*)lds, g, S, E);
.LBB0_314:
	v_readlane_b32 s8, v248, 29
	v_readlane_b32 s9, v248, 30
	v_readlane_b32 s10, v248, 31
	v_readlane_b32 s11, v248, 32
	v_readlane_b32 s12, v248, 33
	v_readlane_b32 s13, v248, 34
	v_readlane_b32 s2, v248, 0
	v_readlane_b32 s14, v248, 35
	v_readlane_b32 s15, v248, 36
	s_mov_b64 s[8:9], s[12:13]
	v_readlane_b32 s3, v248, 1
	s_cmp_lt_i32 s2, 2
	s_mov_b64 s[10:11], s[14:15]
	s_cselect_b64 s[2:3], -1, 0
	s_add_u32 s93, s10, 0x8a00000
	s_addc_u32 s6, s11, 0
	v_writelane_b32 v248, s6, 37
	s_add_u32 s6, s10, 0xaa00000
	v_writelane_b32 v248, s6, 38
	s_addc_u32 s6, s11, 0
	v_writelane_b32 v248, s6, 39
	s_add_u32 s6, s10, 0xcb00000
	v_writelane_b32 v248, s6, 40
	s_addc_u32 s6, s11, 0
	v_writelane_b32 v248, s6, 41
	s_add_u32 s6, s10, 0xec00000
	v_writelane_b32 v248, s6, 42
	s_addc_u32 s6, s11, 0
	v_writelane_b32 v248, s6, 43
	s_add_u32 s6, s10, 0x10c00000
	s_addc_u32 s7, s11, 0
	v_writelane_b32 v248, s6, 44
	s_nop 1
	v_writelane_b32 v248, s7, 45
	s_add_u32 s6, s10, 0x12d00000
	s_addc_u32 s7, s11, 0
	v_writelane_b32 v248, s6, 46
	s_nop 1
	v_writelane_b32 v248, s7, 47
	s_add_u32 s6, s10, 0x14d00000
	s_addc_u32 s7, s11, 0
	v_writelane_b32 v248, s6, 48
	s_nop 1
	v_writelane_b32 v248, s7, 49
	s_add_u32 s6, s10, 0x16d00000
	s_addc_u32 s7, s11, 0
	v_writelane_b32 v248, s6, 50
	s_nop 1
	v_writelane_b32 v248, s7, 51
	s_add_u32 s6, s10, 0x1ed00000
	s_addc_u32 s7, s11, 0
	v_writelane_b32 v248, s6, 52
	s_nop 1
	v_writelane_b32 v248, s7, 53
	s_and_b64 s[6:7], s[2:3], s[0:1]
	s_andn2_b64 vcc, exec, s[6:7]
	s_cbranch_vccnz .LBB0_432
	s_cmpk_lt_i32 s97, 0xa00
	s_cselect_b64 s[0:1], -1, 0
	s_cmpk_gt_i32 s97, 0x9ff
	v_readfirstlane_b32 s12, v186
	s_cbranch_scc1 .LBB0_318
	s_ashr_i32 s2, s97, 31
	s_lshr_b32 s2, s2, 29
	s_add_i32 s2, s97, s2
	s_ashr_i32 s3, s2, 3
	s_and_b32 s2, s2, -8
	s_sub_i32 s2, s97, s2
	s_cmp_lt_i32 s2, 0
	s_movk_i32 s8, 0x141
	s_cselect_b32 s8, s8, 0x140
	s_mul_i32 s2, s2, s8
	s_add_i32 s2, s2, s3
	s_mul_hi_i32 s3, s2, 0x66666667
	s_lshr_b32 s8, s3, 31
	s_ashr_i32 s3, s3, 8
	s_add_i32 s3, s3, s8
	s_lshl_b32 s8, s3, 3
	s_mulk_i32 s3, 0x280
	s_sub_i32 s2, s2, s3
	s_sext_i32_i16 s3, s2
	s_bfe_u32 s3, s3, 0x3001c
	s_add_i32 s3, s2, s3
	s_sext_i32_i16 s9, s3
	s_and_b32 s3, s3, 0xfff8
	s_sub_i32 s2, s2, s3
	s_sext_i32_i16 s2, s2
	s_add_i32 s24, s8, s2
	s_ashr_i32 s2, s9, 3
	s_cmp_ge_u32 s2, 40
	s_cselect_b32 s3, 1, 0
	s_cselect_b32 s9, 40, 0
	s_sub_u32 s2, s2, s9
	s_lshl_b32 s2, s2, 1
	s_or_b32 s2, s2, s3
	s_andn2_b64 vcc, exec, s[0:1]
	v_and_b32_e32 v136, 15, v186
	s_cbranch_vccz .LBB0_319

;     __device__ bool next(int i, Unit& u) const {
;         const int ti = (NSEG == 2) ? (i >> 1) : i; u.seg = (NSEG == 2) ? (i & 1) : 0;
;         const long L = (long)ti * G + c; if (L >= nwg) return false;
;         int wgid = (int)L; { const int q = nwg / NXCD, r = nwg % NXCD, xcd = wgid % NXCD, off = wgid / NXCD; wgid = (xcd < r ? xcd * (q + 1) : r * (q + 1) + (xcd - r) * q) + off; }
;         const int nig = WGM * nN, gid = wgid / nig, fm = gid * WGM, gsz = (nM - fm) < WGM ? (nM - fm) : WGM;
;         u.pm = fm + ((wgid % nig) % gsz); u.pn = (wgid % nig) / gsz; return true;
;     }
; template <class Epi, class Sched, int NSEG, bool ALIGN_EPI = true, bool AFTER_DRAIN = false>
; __device__ __forceinline__ void gemm_phase(LAS unsigned char* lds, const Gemm g, const Sched& S, const Epi& E) {
;     ...
;         const bool has_next = S.next(ui + 1, nxt);
;         const char* nA = has_next ? PG8_ABASE(nxt) : cA; const char* nB = has_next ? PG8_BBASE(nxt) : cB;
;         for (int t = 0; t < nt; t += 2) {
;             const bool last = (t == nt - 2);
;             const char* a1 = cA + (size_t)(t + 1) * kstep;
;             const char* a2 = last ? nA : cA + (size_t)(t + 2) * kstep; const char* b2 = last ? nB : cB + (size_t)(t + 2) * kstep;
;             const char* a3 = a2 + kstep; const char* b3 = b2 + kstep;
;             PG8_LDB(B0, 0, 0); PG8_LDB(B1, 0, 1); PG8_SCHED; PG8_LDA(At, 0, 0); PG8_STAGE(PG8_SA(1, 1), a1 + hstep, voffA);
;             PG8_WAIT_V(8); PG8_WAIT_L(0); PG8_BAR; PG8_MMA(0, 0, At, B0); PG8_MMA(0, 1, At, B1); PG8_BAR; PG8_SCHED;
;             PG8_LDA(At, 0, 1); PG8_STAGE(PG8_SB(0, 0), b2, voffB); PG8_STAGE(PG8_SB(0, 1), b2 + hstep, voffB); PG8_STAGE(PG8_SA(0, 0), a2, voffA);
;             PG8_WAIT_V(8); PG8_WAIT_L(0); PG8_BAR; PG8_MMA(1, 0, At, B0); PG8_MMA(1, 1, At, B1); PG8_BAR; PG8_SCHED;
;             PG8_LDB(B0, 1, 0); PG8_LDB(B1, 1, 1); PG8_SCHED; PG8_LDA(At, 1, 0); PG8_STAGE(PG8_SA(0, 1), a2 + hstep, voffA);
;             PG8_WAIT_V(8); PG8_WAIT_L(0); PG8_BAR; PG8_MMA(0, 0, At, B0); PG8_MMA(0, 1, At, B1); PG8_BAR; PG8_SCHED;
;             PG8_LDA(At, 1, 1); PG8_STAGE(PG8_SB(1, 0), b3, voffB); PG8_STAGE(PG8_SB(1, 1), b3 + hstep, voffB); PG8_STAGE(PG8_SA(1, 0), a3, voffA);
;             PG8_WAIT_V(8); PG8_WAIT_L(0); PG8_BAR; PG8_MMA(1, 0, At, B0); PG8_MMA(1, 1, At, B1); PG8_BAR; PG8_SCHED;
;         }
.LBB0_324:
	s_add_i32 s37, s37, 1
	s_mul_i32 s0, s37, s39
	s_mul_hi_u32 s1, s37, s96
	s_add_i32 s1, s1, s0
	s_mul_i32 s0, s37, s96
	s_add_u32 s20, s0, s97
	s_addc_u32 s21, s1, s40
	v_cmp_gt_i64_e32 vcc, s[20:21], v[156:157]
	v_cmp_lt_i64_e64 s[0:1], s[20:21], v[154:155]
	s_cbranch_vccnz .LBB0_326
	s_ashr_i32 s3, s20, 31
	s_lshr_b32 s3, s3, 29
	s_add_i32 s3, s20, s3
	s_ashr_i32 s16, s3, 3
	s_and_b32 s3, s3, -8
	s_sub_i32 s3, s20, s3
	s_cmp_lt_i32 s3, 0
	s_movk_i32 s17, 0x141
	s_cselect_b32 s17, s17, 0x140
	s_mul_i32 s3, s3, s17
	s_add_i32 s3, s3, s16
	s_mul_hi_i32 s16, s3, 0x66666667
	s_lshr_b32 s17, s16, 31
	s_ashr_i32 s16, s16, 8
	s_add_i32 s16, s16, s17
	s_lshl_b32 s17, s16, 3
	s_sub_i32 s18, 32, s17
	s_min_i32 s18, s18, 8
	s_abs_i32 s19, s18
	v_cvt_f32_u32_e32 v0, s19
	s_sub_i32 s21, 0, s19
	s_mulk_i32 s16, 0x280
	s_sub_i32 s3, s3, s16
	v_rcp_iflag_f32_e32 v0, v0
	s_abs_i32 s16, s3
	s_xor_b32 s20, s3, s18
	s_ashr_i32 s20, s20, 31
	v_mul_f32_e32 v0, 0x4f7ffffe, v0
	v_cvt_u32_f32_e32 v0, v0
	s_nop 0
	v_readfirstlane_b32 s22, v0
	s_mul_i32 s21, s21, s22
	s_mul_hi_u32 s21, s22, s21
	s_add_i32 s22, s22, s21
	s_mul_hi_u32 s21, s16, s22
	s_mul_i32 s22, s21, s19
	s_sub_i32 s16, s16, s22
	s_add_i32 s23, s21, 1
	s_sub_i32 s22, s16, s19
	s_cmp_ge_u32 s16, s19
	s_cselect_b32 s21, s23, s21
	s_cselect_b32 s16, s22, s16
	s_add_i32 s22, s21, 1
	s_cmp_ge_u32 s16, s19
	s_cselect_b32 s16, s22, s21
	s_xor_b32 s16, s16, s20
	s_sub_i32 s16, s16, s20
	s_mul_i32 s18, s16, s18
	s_sub_i32 s3, s3, s18
	s_add_i32 s18, s17, s3
	s_cmp_ge_u32 s16, 40
	s_cselect_b32 s52, 1, 0
	s_cselect_b32 s53, 40, 0
	s_sub_u32 s16, s16, s53
	s_lshl_b32 s16, s16, 1
	s_or_b32 s16, s16, s52
.LBB0_326:
	ds_read_b128 v[192:195], v164 offset:0
	ds_read_b128 v[196:199], v164 offset:1024
	ds_read_b128 v[200:203], v164 offset:2048
	ds_read_b128 v[204:207], v164 offset:3072
	ds_read_b128 v[208:211], v164 offset:4096
	ds_read_b128 v[212:215], v164 offset:5120
	ds_read_b128 v[216:219], v164 offset:6144
	ds_read_b128 v[220:223], v164 offset:7168
	ds_read_b128 v[128:131], v162 offset:0
	ds_read_b128 v[132:135], v162 offset:1024
	ds_read_b128 v[166:169], v162 offset:2048
	ds_read_b128 v[170:173], v162 offset:3072
	s_ashr_i32 s19, s18, 31
	s_lshl_b64 s[20:21], s[18:19], 20
	s_add_u32 s20, s4, s20
	s_addc_u32 s21, s5, s21
	v_readlane_b32 s52, v248, 29
	s_and_b64 s[22:23], s[0:1], exec
	v_readlane_b32 s53, v248, 30
	v_readlane_b32 s54, v248, 31
	v_readlane_b32 s55, v248, 32
	v_readlane_b32 s56, v248, 33
	v_readlane_b32 s57, v248, 34
	s_cselect_b32 s3, s21, s27
	s_cselect_b32 s19, s20, s26
	s_ashr_i32 s17, s16, 31
	v_readlane_b32 s58, v248, 35
	v_readlane_b32 s59, v248, 36
	s_mov_b64 s[52:53], s[56:57]
	s_lshl_b64 s[22:23], s[16:17], 20
	s_mov_b64 s[54:55], s[58:59]
	s_add_u32 s22, s54, s22
	s_addc_u32 s23, s55, s23
	s_and_b64 s[30:31], s[0:1], exec
	s_cselect_b32 s17, s23, s29
	s_cselect_b32 s25, s22, s28
	v_mov_b32_e32 v0, 0
	v_mov_b32_e32 v1, v0
	v_mov_b32_e32 v2, v0
	v_mov_b32_e32 v3, v0
	v_mov_b32_e32 v4, v0
	v_mov_b32_e32 v5, v0
	v_mov_b32_e32 v6, v0
	v_mov_b32_e32 v7, v0
	v_mov_b32_e32 v16, v0
	v_mov_b32_e32 v17, v0
	v_mov_b32_e32 v18, v0
	v_mov_b32_e32 v19, v0
	v_mov_b32_e32 v20, v0
	v_mov_b32_e32 v21, v0
	v_mov_b32_e32 v22, v0
	v_mov_b32_e32 v23, v0
	v_mov_b32_e32 v32, v0
	v_mov_b32_e32 v33, v0
	v_mov_b32_e32 v34, v0
	v_mov_b32_e32 v35, v0
	v_mov_b32_e32 v36, v0
	v_mov_b32_e32 v37, v0
	v_mov_b32_e32 v38, v0
	v_mov_b32_e32 v39, v0
	v_mov_b32_e32 v48, v0
	v_mov_b32_e32 v49, v0
	v_mov_b32_e32 v50, v0
	v_mov_b32_e32 v51, v0
	v_mov_b32_e32 v52, v0
	v_mov_b32_e32 v53, v0
	v_mov_b32_e32 v54, v0
	v_mov_b32_e32 v55, v0
	v_mov_b32_e32 v8, v0
	v_mov_b32_e32 v9, v0
	v_mov_b32_e32 v10, v0
	v_mov_b32_e32 v11, v0
	v_mov_b32_e32 v12, v0
	v_mov_b32_e32 v13, v0
	v_mov_b32_e32 v14, v0
	v_mov_b32_e32 v15, v0
	v_mov_b32_e32 v24, v0
	v_mov_b32_e32 v25, v0
	v_mov_b32_e32 v26, v0
	v_mov_b32_e32 v27, v0
	v_mov_b32_e32 v28, v0
	v_mov_b32_e32 v29, v0
	v_mov_b32_e32 v30, v0
	v_mov_b32_e32 v31, v0
	v_mov_b32_e32 v40, v0
	v_mov_b32_e32 v41, v0
	v_mov_b32_e32 v42, v0
	v_mov_b32_e32 v43, v0
	v_mov_b32_e32 v44, v0
	v_mov_b32_e32 v45, v0
	v_mov_b32_e32 v46, v0
	v_mov_b32_e32 v47, v0
	v_mov_b32_e32 v56, v0
	v_mov_b32_e32 v57, v0
	v_mov_b32_e32 v58, v0
	v_mov_b32_e32 v59, v0
	v_mov_b32_e32 v60, v0
	v_mov_b32_e32 v61, v0
	v_mov_b32_e32 v62, v0
	v_mov_b32_e32 v63, v0
	v_mov_b32_e32 v64, v0
	v_mov_b32_e32 v65, v0
	v_mov_b32_e32 v66, v0
	v_mov_b32_e32 v67, v0
	v_mov_b32_e32 v68, v0
	v_mov_b32_e32 v69, v0
	v_mov_b32_e32 v70, v0
	v_mov_b32_e32 v71, v0
	v_mov_b32_e32 v80, v0
	v_mov_b32_e32 v81, v0
	v_mov_b32_e32 v82, v0
	v_mov_b32_e32 v83, v0
	v_mov_b32_e32 v84, v0
	v_mov_b32_e32 v85, v0
	v_mov_b32_e32 v86, v0
	v_mov_b32_e32 v87, v0
	v_mov_b32_e32 v96, v0
	v_mov_b32_e32 v97, v0
	v_mov_b32_e32 v98, v0
	v_mov_b32_e32 v99, v0
	v_mov_b32_e32 v100, v0
	v_mov_b32_e32 v101, v0
	v_mov_b32_e32 v102, v0
	v_mov_b32_e32 v103, v0
	v_mov_b32_e32 v112, v0
	v_mov_b32_e32 v113, v0
	v_mov_b32_e32 v114, v0
	v_mov_b32_e32 v115, v0
	v_mov_b32_e32 v116, v0
	v_mov_b32_e32 v117, v0
	v_mov_b32_e32 v118, v0
	v_mov_b32_e32 v119, v0
	v_mov_b32_e32 v72, v0
	v_mov_b32_e32 v73, v0
	v_mov_b32_e32 v74, v0
	v_mov_b32_e32 v75, v0
	v_mov_b32_e32 v76, v0
	v_mov_b32_e32 v77, v0
	v_mov_b32_e32 v78, v0
	v_mov_b32_e32 v79, v0
	v_mov_b32_e32 v88, v0
	v_mov_b32_e32 v89, v0
	v_mov_b32_e32 v90, v0
	v_mov_b32_e32 v91, v0
	v_mov_b32_e32 v92, v0
	v_mov_b32_e32 v93, v0
	v_mov_b32_e32 v94, v0
	v_mov_b32_e32 v95, v0
	v_mov_b32_e32 v104, v0
	v_mov_b32_e32 v105, v0
	v_mov_b32_e32 v106, v0
	v_mov_b32_e32 v107, v0
	v_mov_b32_e32 v108, v0
	v_mov_b32_e32 v109, v0
	v_mov_b32_e32 v110, v0
	v_mov_b32_e32 v111, v0
	v_mov_b32_e32 v120, v0
	v_mov_b32_e32 v121, v0
	v_mov_b32_e32 v122, v0
	v_mov_b32_e32 v123, v0
	v_mov_b32_e32 v124, v0
	v_mov_b32_e32 v125, v0
	v_mov_b32_e32 v126, v0
	v_mov_b32_e32 v127, v0
	s_waitcnt lgkmcnt(0)
	s_barrier
	s_cmp_lg_u64 s[8:9], 0
	s_cbranch_scc1 .Lp1_B_entry
	s_mov_b32 s80, 0
	.p2align 6
; #define PG8_STAGE(bufoff, gbase, voff) do { _Pragma("unroll") for (int _i = 0; _i < 2; ++_i) \
;         __builtin_amdgcn_global_load_lds((const unsigned*)((const char*)(gbase) + (voff)[_i]), (LAS unsigned*)(lds + (bufoff) + ldsw + _i * 8192), 16, 0, 0); } while (0)
; #define PG8_LDA(dst, b, h) do { _Pragma("unroll") for (int m = 0; m < 4; ++m) _Pragma("unroll") for (int k = 0; k < 2; ++k) dst[m][k] = *(const LAS bf16x8*)(lds + PG8_SA(b, h) + aoff + m * 2048 + k * 1024); } while (0)
; #define PG8_LDB(dst, b, h) do { _Pragma("unroll") for (int n = 0; n < 2; ++n) _Pragma("unroll") for (int k = 0; k < 2; ++k) dst[n][k] = *(const LAS bf16x8*)(lds + PG8_SB(b, h) + boff + n * 2048 + k * 1024); } while (0)
; #define PG8_MMA(ai, bj, At, Bt) do { __builtin_amdgcn_s_setprio(1); _Pragma("unroll") for (int m = 0; m < 4; ++m) _Pragma("unroll") for (int n = 0; n < 2; ++n) _Pragma("unroll") for (int k = 0; k < 2; ++k) \
;         acc[ai][bj][m][n] = __builtin_amdgcn_mfma_f32_16x16x32_bf16(Bt[n][k], At[m][k], acc[ai][bj][m][n], 0, 0, 0); __builtin_amdgcn_s_setprio(0); } while (0)
; #define PG8_WAIT_V(n) asm volatile("s_waitcnt vmcnt(" #n ")" ::: "memory")
; #define PG8_WAIT_L(n) asm volatile("s_waitcnt lgkmcnt(" #n ")" ::: "memory")
; #define PG8_BAR __builtin_amdgcn_s_barrier()
; template <class Epi, class Sched, int NSEG, bool ALIGN_EPI = true, bool AFTER_DRAIN = false>
; __device__ __forceinline__ void gemm_phase(LAS unsigned char* lds, const Gemm g, const Sched& S, const Epi& E) {
;     ...
;         for (int t = 0; t < nt; t += 2) {
;             const bool last = (t == nt - 2);
;             const char* a1 = cA + (size_t)(t + 1) * kstep;
;             const char* a2 = last ? nA : cA + (size_t)(t + 2) * kstep; const char* b2 = last ? nB : cB + (size_t)(t + 2) * kstep;
;             const char* a3 = a2 + kstep; const char* b3 = b2 + kstep;
;             PG8_LDB(B0, 0, 0); PG8_LDB(B1, 0, 1); PG8_SCHED; PG8_LDA(At, 0, 0); PG8_STAGE(PG8_SA(1, 1), a1 + hstep, voffA);
;             PG8_WAIT_V(8); PG8_WAIT_L(0); PG8_BAR; PG8_MMA(0, 0, At, B0); PG8_MMA(0, 1, At, B1); PG8_BAR; PG8_SCHED;
;             PG8_LDA(At, 0, 1); PG8_STAGE(PG8_SB(0, 0), b2, voffB); PG8_STAGE(PG8_SB(0, 1), b2 + hstep, voffB); PG8_STAGE(PG8_SA(0, 0), a2, voffA);
;             PG8_WAIT_V(8); PG8_WAIT_L(0); PG8_BAR; PG8_MMA(1, 0, At, B0); PG8_MMA(1, 1, At, B1); PG8_BAR; PG8_SCHED;
.Lp1_kloopA:
	s_cmp_eq_u32 s80, 15
	s_cselect_b32 s72, s19, s72
	s_cselect_b32 s73, s3, s73
	s_cselect_b32 s76, s25, s76
	s_cselect_b32 s77, s17, s77
	s_add_u32 s74, s72, 0x80000
	s_addc_u32 s75, s73, 0
	s_add_u32 s78, s76, 0x80000
	s_addc_u32 s79, s77, 0
	v_mfma_f32_16x16x32_bf16 v[124:127], v[128:131], v[192:195], v[124:127]
	s_mov_b32 m0, s33
	ds_read_b128 v[174:177], v162 offset:16384
	v_mfma_f32_16x16x32_bf16 v[120:123], v[166:169], v[192:195], v[120:123]
	global_load_lds_dwordx4 v138, s[72:73]
	ds_read_b128 v[178:181], v162 offset:17408
	v_mfma_f32_16x16x32_bf16 v[108:111], v[128:131], v[200:203], v[108:111]
	s_add_i32 m0, s33, 0x2000
	ds_read_b128 v[182:185], v162 offset:18432
	v_mfma_f32_16x16x32_bf16 v[104:107], v[166:169], v[200:203], v[104:107]
	global_load_lds_dwordx4 v142, s[72:73]
	ds_read_b128 v[188:191], v162 offset:19456
	v_mfma_f32_16x16x32_bf16 v[92:95], v[128:131], v[208:211], v[92:95]
	s_add_i32 m0, s33, 0x10000
	v_mfma_f32_16x16x32_bf16 v[88:91], v[166:169], v[208:211], v[88:91]
	global_load_lds_dwordx4 v140, s[76:77]
	v_mfma_f32_16x16x32_bf16 v[76:79], v[128:131], v[216:219], v[76:79]
	s_add_i32 m0, s33, 0x12000
	v_mfma_f32_16x16x32_bf16 v[72:75], v[166:169], v[216:219], v[72:75]
	global_load_lds_dwordx4 v144, s[76:77]
	v_mfma_f32_16x16x32_bf16 v[124:127], v[132:135], v[196:199], v[124:127]
	ds_read_b128 v[224:227], v164 offset:16384
	v_mfma_f32_16x16x32_bf16 v[120:123], v[170:173], v[196:199], v[120:123]
	ds_read_b128 v[228:231], v164 offset:17408
	v_mfma_f32_16x16x32_bf16 v[108:111], v[132:135], v[204:207], v[108:111]
	ds_read_b128 v[232:235], v164 offset:18432
	v_mfma_f32_16x16x32_bf16 v[104:107], v[170:173], v[204:207], v[104:107]
	ds_read_b128 v[236:239], v164 offset:19456
	v_mfma_f32_16x16x32_bf16 v[92:95], v[132:135], v[212:215], v[92:95]
	ds_read_b128 v[240:243], v164 offset:20480
	v_mfma_f32_16x16x32_bf16 v[88:91], v[170:173], v[212:215], v[88:91]
	ds_read_b128 v[244:247], v164 offset:21504
	v_mfma_f32_16x16x32_bf16 v[76:79], v[132:135], v[220:223], v[76:79]
	ds_read_b128 v[250:253], v164 offset:22528
	v_mfma_f32_16x16x32_bf16 v[72:75], v[170:173], v[220:223], v[72:75]
	ds_read_b128 v[150:153], v164 offset:23552
	s_waitcnt lgkmcnt(8)
	v_mfma_f32_16x16x32_bf16 v[116:119], v[174:177], v[192:195], v[116:119]
	v_mfma_f32_16x16x32_bf16 v[112:115], v[182:185], v[192:195], v[112:115]
	v_mfma_f32_16x16x32_bf16 v[100:103], v[174:177], v[200:203], v[100:103]
	v_mfma_f32_16x16x32_bf16 v[96:99], v[182:185], v[200:203], v[96:99]
	v_mfma_f32_16x16x32_bf16 v[84:87], v[174:177], v[208:211], v[84:87]
	v_mfma_f32_16x16x32_bf16 v[80:83], v[182:185], v[208:211], v[80:83]
	v_mfma_f32_16x16x32_bf16 v[68:71], v[174:177], v[216:219], v[68:71]
	v_mfma_f32_16x16x32_bf16 v[64:67], v[182:185], v[216:219], v[64:67]
	v_mfma_f32_16x16x32_bf16 v[116:119], v[178:181], v[196:199], v[116:119]
	v_mfma_f32_16x16x32_bf16 v[112:115], v[188:191], v[196:199], v[112:115]
	v_mfma_f32_16x16x32_bf16 v[100:103], v[178:181], v[204:207], v[100:103]
	v_mfma_f32_16x16x32_bf16 v[96:99], v[188:191], v[204:207], v[96:99]
	v_mfma_f32_16x16x32_bf16 v[84:87], v[178:181], v[212:215], v[84:87]
	v_mfma_f32_16x16x32_bf16 v[80:83], v[188:191], v[212:215], v[80:83]
	v_mfma_f32_16x16x32_bf16 v[68:71], v[178:181], v[220:223], v[68:71]
	v_mfma_f32_16x16x32_bf16 v[64:67], v[188:191], v[220:223], v[64:67]
	s_waitcnt vmcnt(8) lgkmcnt(0)
	s_barrier
	v_mfma_f32_16x16x32_bf16 v[60:63], v[128:131], v[224:227], v[60:63]
	s_add_i32 m0, s33, 0x4000
	v_mfma_f32_16x16x32_bf16 v[56:59], v[166:169], v[224:227], v[56:59]
	global_load_lds_dwordx4 v138, s[74:75]
	v_mfma_f32_16x16x32_bf16 v[44:47], v[128:131], v[232:235], v[44:47]
	s_add_i32 m0, s33, 0x6000
	v_mfma_f32_16x16x32_bf16 v[40:43], v[166:169], v[232:235], v[40:43]
	global_load_lds_dwordx4 v142, s[74:75]
	v_mfma_f32_16x16x32_bf16 v[28:31], v[128:131], v[240:243], v[28:31]
	s_add_i32 m0, s33, 0x14000
	v_mfma_f32_16x16x32_bf16 v[24:27], v[166:169], v[240:243], v[24:27]
	global_load_lds_dwordx4 v140, s[78:79]
	v_mfma_f32_16x16x32_bf16 v[12:15], v[128:131], v[250:253], v[12:15]
	s_add_i32 m0, s33, 0x16000
	v_mfma_f32_16x16x32_bf16 v[8:11], v[166:169], v[250:253], v[8:11]
	global_load_lds_dwordx4 v144, s[78:79]
	v_mfma_f32_16x16x32_bf16 v[60:63], v[132:135], v[228:231], v[60:63]
	ds_read_b128 v[192:195], v164 offset:32768
	v_mfma_f32_16x16x32_bf16 v[56:59], v[170:173], v[228:231], v[56:59]
	ds_read_b128 v[196:199], v164 offset:33792
	v_mfma_f32_16x16x32_bf16 v[44:47], v[132:135], v[236:239], v[44:47]
	ds_read_b128 v[200:203], v164 offset:34816
	v_mfma_f32_16x16x32_bf16 v[40:43], v[170:173], v[236:239], v[40:43]
	ds_read_b128 v[204:207], v164 offset:35840
	v_mfma_f32_16x16x32_bf16 v[28:31], v[132:135], v[244:247], v[28:31]
	ds_read_b128 v[208:211], v164 offset:36864
	v_mfma_f32_16x16x32_bf16 v[24:27], v[170:173], v[244:247], v[24:27]
	ds_read_b128 v[212:215], v164 offset:37888
	v_mfma_f32_16x16x32_bf16 v[12:15], v[132:135], v[150:153], v[12:15]
	ds_read_b128 v[216:219], v164 offset:38912
	v_mfma_f32_16x16x32_bf16 v[8:11], v[170:173], v[150:153], v[8:11]
	ds_read_b128 v[220:223], v164 offset:39936
	v_mfma_f32_16x16x32_bf16 v[52:55], v[174:177], v[224:227], v[52:55]
	ds_read_b128 v[128:131], v162 offset:32768
	v_mfma_f32_16x16x32_bf16 v[48:51], v[182:185], v[224:227], v[48:51]
	ds_read_b128 v[132:135], v162 offset:33792
	v_mfma_f32_16x16x32_bf16 v[36:39], v[174:177], v[232:235], v[36:39]
	ds_read_b128 v[166:169], v162 offset:34816
	v_mfma_f32_16x16x32_bf16 v[32:35], v[182:185], v[232:235], v[32:35]
	ds_read_b128 v[170:173], v162 offset:35840
	v_mfma_f32_16x16x32_bf16 v[20:23], v[174:177], v[240:243], v[20:23]
	v_mfma_f32_16x16x32_bf16 v[16:19], v[182:185], v[240:243], v[16:19]
	v_mfma_f32_16x16x32_bf16 v[4:7], v[174:177], v[250:253], v[4:7]
	v_mfma_f32_16x16x32_bf16 v[0:3], v[182:185], v[250:253], v[0:3]
	v_mfma_f32_16x16x32_bf16 v[52:55], v[178:181], v[228:231], v[52:55]
	v_mfma_f32_16x16x32_bf16 v[48:51], v[188:191], v[228:231], v[48:51]
	v_mfma_f32_16x16x32_bf16 v[36:39], v[178:181], v[236:239], v[36:39]
	v_mfma_f32_16x16x32_bf16 v[32:35], v[188:191], v[236:239], v[32:35]
	v_mfma_f32_16x16x32_bf16 v[20:23], v[178:181], v[244:247], v[20:23]
	v_mfma_f32_16x16x32_bf16 v[16:19], v[188:191], v[244:247], v[16:19]
	v_mfma_f32_16x16x32_bf16 v[4:7], v[178:181], v[150:153], v[4:7]
	v_mfma_f32_16x16x32_bf16 v[0:3], v[188:191], v[150:153], v[0:3]
	s_waitcnt vmcnt(8) lgkmcnt(0)
	s_barrier
; #define PG8_STAGE(bufoff, gbase, voff) do { _Pragma("unroll") for (int _i = 0; _i < 2; ++_i) \
;         __builtin_amdgcn_global_load_lds((const unsigned*)((const char*)(gbase) + (voff)[_i]), (LAS unsigned*)(lds + (bufoff) + ldsw + _i * 8192), 16, 0, 0); } while (0)
; #define PG8_LDA(dst, b, h) do { _Pragma("unroll") for (int m = 0; m < 4; ++m) _Pragma("unroll") for (int k = 0; k < 2; ++k) dst[m][k] = *(const LAS bf16x8*)(lds + PG8_SA(b, h) + aoff + m * 2048 + k * 1024); } while (0)
; #define PG8_LDB(dst, b, h) do { _Pragma("unroll") for (int n = 0; n < 2; ++n) _Pragma("unroll") for (int k = 0; k < 2; ++k) dst[n][k] = *(const LAS bf16x8*)(lds + PG8_SB(b, h) + boff + n * 2048 + k * 1024); } while (0)
; #define PG8_MMA(ai, bj, At, Bt) do { __builtin_amdgcn_s_setprio(1); _Pragma("unroll") for (int m = 0; m < 4; ++m) _Pragma("unroll") for (int n = 0; n < 2; ++n) _Pragma("unroll") for (int k = 0; k < 2; ++k) \
;         acc[ai][bj][m][n] = __builtin_amdgcn_mfma_f32_16x16x32_bf16(Bt[n][k], At[m][k], acc[ai][bj][m][n], 0, 0, 0); __builtin_amdgcn_s_setprio(0); } while (0)
; #define PG8_WAIT_V(n) asm volatile("s_waitcnt vmcnt(" #n ")" ::: "memory")
; #define PG8_WAIT_L(n) asm volatile("s_waitcnt lgkmcnt(" #n ")" ::: "memory")
; #define PG8_BAR __builtin_amdgcn_s_barrier()
; #define PG8_SCHED __builtin_amdgcn_sched_barrier(0)
; template <class Epi, class Sched, int NSEG, bool ALIGN_EPI = true, bool AFTER_DRAIN = false>
; __device__ __forceinline__ void gemm_phase(LAS unsigned char* lds, const Gemm g, const Sched& S, const Epi& E) {
;     ...
;             PG8_LDB(B0, 1, 0); PG8_LDB(B1, 1, 1); PG8_SCHED; PG8_LDA(At, 1, 0); PG8_STAGE(PG8_SA(0, 1), a2 + hstep, voffA);
;             PG8_WAIT_V(8); PG8_WAIT_L(0); PG8_BAR; PG8_MMA(0, 0, At, B0); PG8_MMA(0, 1, At, B1); PG8_BAR; PG8_SCHED;
;             PG8_LDA(At, 1, 1); PG8_STAGE(PG8_SB(1, 0), b3, voffB); PG8_STAGE(PG8_SB(1, 1), b3 + hstep, voffB); PG8_STAGE(PG8_SA(1, 0), a3, voffA);
;             PG8_WAIT_V(8); PG8_WAIT_L(0); PG8_BAR; PG8_MMA(1, 0, At, B0); PG8_MMA(1, 1, At, B1); PG8_BAR; PG8_SCHED;
;         }
	v_mfma_f32_16x16x32_bf16 v[124:127], v[128:131], v[192:195], v[124:127]
	s_add_i32 m0, s33, 0x8000
	ds_read_b128 v[174:177], v162 offset:49152
	s_add_u32 s72, s72, 0x80
	s_addc_u32 s73, s73, 0
	v_mfma_f32_16x16x32_bf16 v[120:123], v[166:169], v[192:195], v[120:123]
	global_load_lds_dwordx4 v138, s[72:73]
	ds_read_b128 v[178:181], v162 offset:50176
	s_add_u32 s76, s76, 0x80
	s_addc_u32 s77, s77, 0
	v_mfma_f32_16x16x32_bf16 v[108:111], v[128:131], v[200:203], v[108:111]
	s_add_i32 m0, s33, 0xa000
	ds_read_b128 v[182:185], v162 offset:51200
	v_mfma_f32_16x16x32_bf16 v[104:107], v[166:169], v[200:203], v[104:107]
	global_load_lds_dwordx4 v142, s[72:73]
	ds_read_b128 v[188:191], v162 offset:52224
	v_mfma_f32_16x16x32_bf16 v[92:95], v[128:131], v[208:211], v[92:95]
	s_add_i32 m0, s33, 0x18000
	v_mfma_f32_16x16x32_bf16 v[88:91], v[166:169], v[208:211], v[88:91]
	global_load_lds_dwordx4 v140, s[76:77]
	v_mfma_f32_16x16x32_bf16 v[76:79], v[128:131], v[216:219], v[76:79]
	s_add_i32 m0, s33, 0x1a000
	v_mfma_f32_16x16x32_bf16 v[72:75], v[166:169], v[216:219], v[72:75]
	global_load_lds_dwordx4 v144, s[76:77]
	v_mfma_f32_16x16x32_bf16 v[124:127], v[132:135], v[196:199], v[124:127]
	ds_read_b128 v[224:227], v164 offset:49152
	v_mfma_f32_16x16x32_bf16 v[120:123], v[170:173], v[196:199], v[120:123]
	ds_read_b128 v[228:231], v164 offset:50176
	v_mfma_f32_16x16x32_bf16 v[108:111], v[132:135], v[204:207], v[108:111]
	ds_read_b128 v[232:235], v164 offset:51200
	v_mfma_f32_16x16x32_bf16 v[104:107], v[170:173], v[204:207], v[104:107]
	ds_read_b128 v[236:239], v164 offset:52224
	v_mfma_f32_16x16x32_bf16 v[92:95], v[132:135], v[212:215], v[92:95]
	ds_read_b128 v[240:243], v164 offset:53248
	v_mfma_f32_16x16x32_bf16 v[88:91], v[170:173], v[212:215], v[88:91]
	ds_read_b128 v[244:247], v164 offset:54272
	v_mfma_f32_16x16x32_bf16 v[76:79], v[132:135], v[220:223], v[76:79]
	ds_read_b128 v[250:253], v164 offset:55296
	v_mfma_f32_16x16x32_bf16 v[72:75], v[170:173], v[220:223], v[72:75]
	ds_read_b128 v[150:153], v164 offset:56320
	s_waitcnt lgkmcnt(8)
	v_mfma_f32_16x16x32_bf16 v[116:119], v[174:177], v[192:195], v[116:119]
	v_mfma_f32_16x16x32_bf16 v[112:115], v[182:185], v[192:195], v[112:115]
	v_mfma_f32_16x16x32_bf16 v[100:103], v[174:177], v[200:203], v[100:103]
	v_mfma_f32_16x16x32_bf16 v[96:99], v[182:185], v[200:203], v[96:99]
	v_mfma_f32_16x16x32_bf16 v[84:87], v[174:177], v[208:211], v[84:87]
	v_mfma_f32_16x16x32_bf16 v[80:83], v[182:185], v[208:211], v[80:83]
	v_mfma_f32_16x16x32_bf16 v[68:71], v[174:177], v[216:219], v[68:71]
	v_mfma_f32_16x16x32_bf16 v[64:67], v[182:185], v[216:219], v[64:67]
	v_mfma_f32_16x16x32_bf16 v[116:119], v[178:181], v[196:199], v[116:119]
	s_add_u32 s74, s74, 0x80
	s_addc_u32 s75, s75, 0
	v_mfma_f32_16x16x32_bf16 v[112:115], v[188:191], v[196:199], v[112:115]
	s_add_u32 s78, s78, 0x80
	s_addc_u32 s79, s79, 0
	v_mfma_f32_16x16x32_bf16 v[100:103], v[178:181], v[204:207], v[100:103]
	v_mfma_f32_16x16x32_bf16 v[96:99], v[188:191], v[204:207], v[96:99]
	v_mfma_f32_16x16x32_bf16 v[84:87], v[178:181], v[212:215], v[84:87]
	v_mfma_f32_16x16x32_bf16 v[80:83], v[188:191], v[212:215], v[80:83]
	v_mfma_f32_16x16x32_bf16 v[68:71], v[178:181], v[220:223], v[68:71]
	v_mfma_f32_16x16x32_bf16 v[64:67], v[188:191], v[220:223], v[64:67]
	s_waitcnt vmcnt(8) lgkmcnt(0)
	s_barrier
	v_mfma_f32_16x16x32_bf16 v[60:63], v[128:131], v[224:227], v[60:63]
	s_add_i32 m0, s33, 0xc000
	v_mfma_f32_16x16x32_bf16 v[56:59], v[166:169], v[224:227], v[56:59]
	global_load_lds_dwordx4 v138, s[74:75]
	v_mfma_f32_16x16x32_bf16 v[44:47], v[128:131], v[232:235], v[44:47]
	s_add_i32 m0, s33, 0xe000
	v_mfma_f32_16x16x32_bf16 v[40:43], v[166:169], v[232:235], v[40:43]
	global_load_lds_dwordx4 v142, s[74:75]
	v_mfma_f32_16x16x32_bf16 v[28:31], v[128:131], v[240:243], v[28:31]
	s_add_i32 m0, s33, 0x1c000
	v_mfma_f32_16x16x32_bf16 v[24:27], v[166:169], v[240:243], v[24:27]
	global_load_lds_dwordx4 v140, s[78:79]
	v_mfma_f32_16x16x32_bf16 v[12:15], v[128:131], v[250:253], v[12:15]
	s_add_i32 m0, s33, 0x1e000
	v_mfma_f32_16x16x32_bf16 v[8:11], v[166:169], v[250:253], v[8:11]
	global_load_lds_dwordx4 v144, s[78:79]
	v_mfma_f32_16x16x32_bf16 v[60:63], v[132:135], v[228:231], v[60:63]
	ds_read_b128 v[192:195], v164 offset:0
	v_mfma_f32_16x16x32_bf16 v[56:59], v[170:173], v[228:231], v[56:59]
	ds_read_b128 v[196:199], v164 offset:1024
	v_mfma_f32_16x16x32_bf16 v[44:47], v[132:135], v[236:239], v[44:47]
	ds_read_b128 v[200:203], v164 offset:2048
	v_mfma_f32_16x16x32_bf16 v[40:43], v[170:173], v[236:239], v[40:43]
	ds_read_b128 v[204:207], v164 offset:3072
	v_mfma_f32_16x16x32_bf16 v[28:31], v[132:135], v[244:247], v[28:31]
	ds_read_b128 v[208:211], v164 offset:4096
	v_mfma_f32_16x16x32_bf16 v[24:27], v[170:173], v[244:247], v[24:27]
	ds_read_b128 v[212:215], v164 offset:5120
	v_mfma_f32_16x16x32_bf16 v[12:15], v[132:135], v[150:153], v[12:15]
	ds_read_b128 v[216:219], v164 offset:6144
	v_mfma_f32_16x16x32_bf16 v[8:11], v[170:173], v[150:153], v[8:11]
	ds_read_b128 v[220:223], v164 offset:7168
	v_mfma_f32_16x16x32_bf16 v[52:55], v[174:177], v[224:227], v[52:55]
	ds_read_b128 v[128:131], v162 offset:0
	v_mfma_f32_16x16x32_bf16 v[48:51], v[182:185], v[224:227], v[48:51]
	ds_read_b128 v[132:135], v162 offset:1024
	v_mfma_f32_16x16x32_bf16 v[36:39], v[174:177], v[232:235], v[36:39]
	ds_read_b128 v[166:169], v162 offset:2048
	v_mfma_f32_16x16x32_bf16 v[32:35], v[182:185], v[232:235], v[32:35]
	ds_read_b128 v[170:173], v162 offset:3072
	v_mfma_f32_16x16x32_bf16 v[20:23], v[174:177], v[240:243], v[20:23]
	v_mfma_f32_16x16x32_bf16 v[16:19], v[182:185], v[240:243], v[16:19]
	v_mfma_f32_16x16x32_bf16 v[4:7], v[174:177], v[250:253], v[4:7]
	v_mfma_f32_16x16x32_bf16 v[0:3], v[182:185], v[250:253], v[0:3]
	v_mfma_f32_16x16x32_bf16 v[52:55], v[178:181], v[228:231], v[52:55]
	v_mfma_f32_16x16x32_bf16 v[48:51], v[188:191], v[228:231], v[48:51]
	v_mfma_f32_16x16x32_bf16 v[36:39], v[178:181], v[236:239], v[36:39]
	v_mfma_f32_16x16x32_bf16 v[32:35], v[188:191], v[236:239], v[32:35]
	s_add_u32 s72, s72, 0x80
	s_addc_u32 s73, s73, 0
	v_mfma_f32_16x16x32_bf16 v[20:23], v[178:181], v[244:247], v[20:23]
	s_add_u32 s76, s76, 0x80
	s_addc_u32 s77, s77, 0
	v_mfma_f32_16x16x32_bf16 v[16:19], v[188:191], v[244:247], v[16:19]
	s_add_i32 s80, s80, 1
	v_mfma_f32_16x16x32_bf16 v[4:7], v[178:181], v[150:153], v[4:7]
	v_mfma_f32_16x16x32_bf16 v[0:3], v[188:191], v[150:153], v[0:3]
	s_waitcnt vmcnt(8) lgkmcnt(0)
	s_barrier
	s_cmp_lt_u32 s80, 16
	s_cbranch_scc1 .Lp1_kloopA
	s_nop 7
	s_branch .Lp1_exit
; #define PG8_STAGE(bufoff, gbase, voff) do { _Pragma("unroll") for (int _i = 0; _i < 2; ++_i) \
;         __builtin_amdgcn_global_load_lds((const unsigned*)((const char*)(gbase) + (voff)[_i]), (LAS unsigned*)(lds + (bufoff) + ldsw + _i * 8192), 16, 0, 0); } while (0)
; #define PG8_LDA(dst, b, h) do { _Pragma("unroll") for (int m = 0; m < 4; ++m) _Pragma("unroll") for (int k = 0; k < 2; ++k) dst[m][k] = *(const LAS bf16x8*)(lds + PG8_SA(b, h) + aoff + m * 2048 + k * 1024); } while (0)
; #define PG8_LDB(dst, b, h) do { _Pragma("unroll") for (int n = 0; n < 2; ++n) _Pragma("unroll") for (int k = 0; k < 2; ++k) dst[n][k] = *(const LAS bf16x8*)(lds + PG8_SB(b, h) + boff + n * 2048 + k * 1024); } while (0)
; #define PG8_MMA(ai, bj, At, Bt) do { __builtin_amdgcn_s_setprio(1); _Pragma("unroll") for (int m = 0; m < 4; ++m) _Pragma("unroll") for (int n = 0; n < 2; ++n) _Pragma("unroll") for (int k = 0; k < 2; ++k) \
;         acc[ai][bj][m][n] = __builtin_amdgcn_mfma_f32_16x16x32_bf16(Bt[n][k], At[m][k], acc[ai][bj][m][n], 0, 0, 0); __builtin_amdgcn_s_setprio(0); } while (0)
; #define PG8_WAIT_V(n) asm volatile("s_waitcnt vmcnt(" #n ")" ::: "memory")
; #define PG8_WAIT_L(n) asm volatile("s_waitcnt lgkmcnt(" #n ")" ::: "memory")
; #define PG8_BAR __builtin_amdgcn_s_barrier()
; template <class Epi, class Sched, int NSEG, bool ALIGN_EPI = true, bool AFTER_DRAIN = false>
; __device__ __forceinline__ void gemm_phase(LAS unsigned char* lds, const Gemm g, const Sched& S, const Epi& E) {
;     ...
;         for (int t = 0; t < nt; t += 2) {
;             const bool last = (t == nt - 2);
;             const char* a1 = cA + (size_t)(t + 1) * kstep;
;             const char* a2 = last ? nA : cA + (size_t)(t + 2) * kstep; const char* b2 = last ? nB : cB + (size_t)(t + 2) * kstep;
;             const char* a3 = a2 + kstep; const char* b3 = b2 + kstep;
;             PG8_LDB(B0, 0, 0); PG8_LDB(B1, 0, 1); PG8_SCHED; PG8_LDA(At, 0, 0); PG8_STAGE(PG8_SA(1, 1), a1 + hstep, voffA);
;             PG8_WAIT_V(8); PG8_WAIT_L(0); PG8_BAR; PG8_MMA(0, 0, At, B0); PG8_MMA(0, 1, At, B1); PG8_BAR; PG8_SCHED;
;             PG8_LDA(At, 0, 1); PG8_STAGE(PG8_SB(0, 0), b2, voffB); PG8_STAGE(PG8_SB(0, 1), b2 + hstep, voffB); PG8_STAGE(PG8_SA(0, 0), a2, voffA);
;             PG8_WAIT_V(8); PG8_WAIT_L(0); PG8_BAR; PG8_MMA(1, 0, At, B0); PG8_MMA(1, 1, At, B1); PG8_BAR; PG8_SCHED;
.Lp1_B_entry:
	s_mov_b32 s80, 0
	.p2align 6
.Lp1_kloopB:
	s_cmp_eq_u32 s80, 15
	s_cselect_b32 s72, s19, s72
	s_cselect_b32 s73, s3, s73
	s_cselect_b32 s76, s25, s76
	s_cselect_b32 s77, s17, s77
	s_add_u32 s74, s72, 0x80000
	s_addc_u32 s75, s73, 0
	s_add_u32 s78, s76, 0x80000
	s_addc_u32 s79, s77, 0
	v_mfma_f32_16x16x32_bf16 v[124:127], v[128:131], v[192:195], v[124:127]
	ds_read_b128 v[174:177], v162 offset:16384
	v_mfma_f32_16x16x32_bf16 v[120:123], v[166:169], v[192:195], v[120:123]
	ds_read_b128 v[178:181], v162 offset:17408
	v_mfma_f32_16x16x32_bf16 v[108:111], v[128:131], v[200:203], v[108:111]
	ds_read_b128 v[182:185], v162 offset:18432
	v_mfma_f32_16x16x32_bf16 v[104:107], v[166:169], v[200:203], v[104:107]
	ds_read_b128 v[188:191], v162 offset:19456
	v_mfma_f32_16x16x32_bf16 v[92:95], v[128:131], v[208:211], v[92:95]
	ds_read_b128 v[224:227], v164 offset:16384
	v_mfma_f32_16x16x32_bf16 v[88:91], v[166:169], v[208:211], v[88:91]
	ds_read_b128 v[228:231], v164 offset:17408
	v_mfma_f32_16x16x32_bf16 v[76:79], v[128:131], v[216:219], v[76:79]
	ds_read_b128 v[232:235], v164 offset:18432
	v_mfma_f32_16x16x32_bf16 v[72:75], v[166:169], v[216:219], v[72:75]
	ds_read_b128 v[236:239], v164 offset:19456
	v_mfma_f32_16x16x32_bf16 v[124:127], v[132:135], v[196:199], v[124:127]
	ds_read_b128 v[240:243], v164 offset:20480
	v_mfma_f32_16x16x32_bf16 v[120:123], v[170:173], v[196:199], v[120:123]
	ds_read_b128 v[244:247], v164 offset:21504
	v_mfma_f32_16x16x32_bf16 v[108:111], v[132:135], v[204:207], v[108:111]
	ds_read_b128 v[250:253], v164 offset:22528
	v_mfma_f32_16x16x32_bf16 v[104:107], v[170:173], v[204:207], v[104:107]
	ds_read_b128 v[150:153], v164 offset:23552
	v_mfma_f32_16x16x32_bf16 v[92:95], v[132:135], v[212:215], v[92:95]
	v_mfma_f32_16x16x32_bf16 v[88:91], v[170:173], v[212:215], v[88:91]
	v_mfma_f32_16x16x32_bf16 v[76:79], v[132:135], v[220:223], v[76:79]
	v_mfma_f32_16x16x32_bf16 v[72:75], v[170:173], v[220:223], v[72:75]
	s_waitcnt lgkmcnt(8)
	v_mfma_f32_16x16x32_bf16 v[116:119], v[174:177], v[192:195], v[116:119]
	v_mfma_f32_16x16x32_bf16 v[112:115], v[182:185], v[192:195], v[112:115]
	s_mov_b32 m0, s33
	v_mfma_f32_16x16x32_bf16 v[100:103], v[174:177], v[200:203], v[100:103]
	global_load_lds_dwordx4 v138, s[72:73]
	v_mfma_f32_16x16x32_bf16 v[96:99], v[182:185], v[200:203], v[96:99]
	s_add_i32 m0, s33, 0x2000
	v_mfma_f32_16x16x32_bf16 v[84:87], v[174:177], v[208:211], v[84:87]
	global_load_lds_dwordx4 v142, s[72:73]
	v_mfma_f32_16x16x32_bf16 v[80:83], v[182:185], v[208:211], v[80:83]
	s_add_i32 m0, s33, 0x10000
	v_mfma_f32_16x16x32_bf16 v[68:71], v[174:177], v[216:219], v[68:71]
	global_load_lds_dwordx4 v140, s[76:77]
	v_mfma_f32_16x16x32_bf16 v[64:67], v[182:185], v[216:219], v[64:67]
	s_add_i32 m0, s33, 0x12000
	v_mfma_f32_16x16x32_bf16 v[116:119], v[178:181], v[196:199], v[116:119]
	global_load_lds_dwordx4 v144, s[76:77]
	v_mfma_f32_16x16x32_bf16 v[112:115], v[188:191], v[196:199], v[112:115]
	v_mfma_f32_16x16x32_bf16 v[100:103], v[178:181], v[204:207], v[100:103]
	v_mfma_f32_16x16x32_bf16 v[96:99], v[188:191], v[204:207], v[96:99]
	v_mfma_f32_16x16x32_bf16 v[84:87], v[178:181], v[212:215], v[84:87]
	v_mfma_f32_16x16x32_bf16 v[80:83], v[188:191], v[212:215], v[80:83]
	v_mfma_f32_16x16x32_bf16 v[68:71], v[178:181], v[220:223], v[68:71]
	v_mfma_f32_16x16x32_bf16 v[64:67], v[188:191], v[220:223], v[64:67]
	s_waitcnt vmcnt(8) lgkmcnt(0)
	s_barrier
	v_mfma_f32_16x16x32_bf16 v[60:63], v[128:131], v[224:227], v[60:63]
	ds_read_b128 v[192:195], v164 offset:32768
	v_mfma_f32_16x16x32_bf16 v[56:59], v[166:169], v[224:227], v[56:59]
	ds_read_b128 v[196:199], v164 offset:33792
	v_mfma_f32_16x16x32_bf16 v[44:47], v[128:131], v[232:235], v[44:47]
	ds_read_b128 v[200:203], v164 offset:34816
	v_mfma_f32_16x16x32_bf16 v[40:43], v[166:169], v[232:235], v[40:43]
	ds_read_b128 v[204:207], v164 offset:35840
	v_mfma_f32_16x16x32_bf16 v[28:31], v[128:131], v[240:243], v[28:31]
	ds_read_b128 v[208:211], v164 offset:36864
	v_mfma_f32_16x16x32_bf16 v[24:27], v[166:169], v[240:243], v[24:27]
	ds_read_b128 v[212:215], v164 offset:37888
	v_mfma_f32_16x16x32_bf16 v[12:15], v[128:131], v[250:253], v[12:15]
	ds_read_b128 v[216:219], v164 offset:38912
	v_mfma_f32_16x16x32_bf16 v[8:11], v[166:169], v[250:253], v[8:11]
	ds_read_b128 v[220:223], v164 offset:39936
	v_mfma_f32_16x16x32_bf16 v[60:63], v[132:135], v[228:231], v[60:63]
	v_mfma_f32_16x16x32_bf16 v[56:59], v[170:173], v[228:231], v[56:59]
	v_mfma_f32_16x16x32_bf16 v[44:47], v[132:135], v[236:239], v[44:47]
	v_mfma_f32_16x16x32_bf16 v[40:43], v[170:173], v[236:239], v[40:43]
	v_mfma_f32_16x16x32_bf16 v[28:31], v[132:135], v[244:247], v[28:31]
	v_mfma_f32_16x16x32_bf16 v[24:27], v[170:173], v[244:247], v[24:27]
	v_mfma_f32_16x16x32_bf16 v[12:15], v[132:135], v[150:153], v[12:15]
	v_mfma_f32_16x16x32_bf16 v[8:11], v[170:173], v[150:153], v[8:11]
	v_mfma_f32_16x16x32_bf16 v[52:55], v[174:177], v[224:227], v[52:55]
	v_mfma_f32_16x16x32_bf16 v[48:51], v[182:185], v[224:227], v[48:51]
	s_add_i32 m0, s33, 0x4000
	v_mfma_f32_16x16x32_bf16 v[36:39], v[174:177], v[232:235], v[36:39]
	global_load_lds_dwordx4 v138, s[74:75]
	v_mfma_f32_16x16x32_bf16 v[32:35], v[182:185], v[232:235], v[32:35]
	s_add_i32 m0, s33, 0x6000
	v_mfma_f32_16x16x32_bf16 v[20:23], v[174:177], v[240:243], v[20:23]
	global_load_lds_dwordx4 v142, s[74:75]
	v_mfma_f32_16x16x32_bf16 v[16:19], v[182:185], v[240:243], v[16:19]
	s_add_i32 m0, s33, 0x14000
	v_mfma_f32_16x16x32_bf16 v[4:7], v[174:177], v[250:253], v[4:7]
	global_load_lds_dwordx4 v140, s[78:79]
	v_mfma_f32_16x16x32_bf16 v[0:3], v[182:185], v[250:253], v[0:3]
	s_add_i32 m0, s33, 0x16000
	v_mfma_f32_16x16x32_bf16 v[52:55], v[178:181], v[228:231], v[52:55]
	global_load_lds_dwordx4 v144, s[78:79]
	v_mfma_f32_16x16x32_bf16 v[48:51], v[188:191], v[228:231], v[48:51]
	v_mfma_f32_16x16x32_bf16 v[36:39], v[178:181], v[236:239], v[36:39]
	ds_read_b128 v[128:131], v162 offset:32768
	v_mfma_f32_16x16x32_bf16 v[32:35], v[188:191], v[236:239], v[32:35]
	ds_read_b128 v[132:135], v162 offset:33792
	v_mfma_f32_16x16x32_bf16 v[20:23], v[178:181], v[244:247], v[20:23]
	ds_read_b128 v[166:169], v162 offset:34816
	v_mfma_f32_16x16x32_bf16 v[16:19], v[188:191], v[244:247], v[16:19]
	ds_read_b128 v[170:173], v162 offset:35840
	v_mfma_f32_16x16x32_bf16 v[4:7], v[178:181], v[150:153], v[4:7]
	v_mfma_f32_16x16x32_bf16 v[0:3], v[188:191], v[150:153], v[0:3]
	s_waitcnt vmcnt(8) lgkmcnt(0)
	s_barrier
; #define PG8_STAGE(bufoff, gbase, voff) do { _Pragma("unroll") for (int _i = 0; _i < 2; ++_i) \
;         __builtin_amdgcn_global_load_lds((const unsigned*)((const char*)(gbase) + (voff)[_i]), (LAS unsigned*)(lds + (bufoff) + ldsw + _i * 8192), 16, 0, 0); } while (0)
; #define PG8_LDA(dst, b, h) do { _Pragma("unroll") for (int m = 0; m < 4; ++m) _Pragma("unroll") for (int k = 0; k < 2; ++k) dst[m][k] = *(const LAS bf16x8*)(lds + PG8_SA(b, h) + aoff + m * 2048 + k * 1024); } while (0)
; #define PG8_LDB(dst, b, h) do { _Pragma("unroll") for (int n = 0; n < 2; ++n) _Pragma("unroll") for (int k = 0; k < 2; ++k) dst[n][k] = *(const LAS bf16x8*)(lds + PG8_SB(b, h) + boff + n * 2048 + k * 1024); } while (0)
; #define PG8_MMA(ai, bj, At, Bt) do { __builtin_amdgcn_s_setprio(1); _Pragma("unroll") for (int m = 0; m < 4; ++m) _Pragma("unroll") for (int n = 0; n < 2; ++n) _Pragma("unroll") for (int k = 0; k < 2; ++k) \
;         acc[ai][bj][m][n] = __builtin_amdgcn_mfma_f32_16x16x32_bf16(Bt[n][k], At[m][k], acc[ai][bj][m][n], 0, 0, 0); __builtin_amdgcn_s_setprio(0); } while (0)
; #define PG8_WAIT_V(n) asm volatile("s_waitcnt vmcnt(" #n ")" ::: "memory")
; #define PG8_WAIT_L(n) asm volatile("s_waitcnt lgkmcnt(" #n ")" ::: "memory")
; #define PG8_BAR __builtin_amdgcn_s_barrier()
; #define PG8_SCHED __builtin_amdgcn_sched_barrier(0)
; template <class Epi, class Sched, int NSEG, bool ALIGN_EPI = true, bool AFTER_DRAIN = false>
; __device__ __forceinline__ void gemm_phase(LAS unsigned char* lds, const Gemm g, const Sched& S, const Epi& E) {
;     ...
;             PG8_LDB(B0, 1, 0); PG8_LDB(B1, 1, 1); PG8_SCHED; PG8_LDA(At, 1, 0); PG8_STAGE(PG8_SA(0, 1), a2 + hstep, voffA);
;             PG8_WAIT_V(8); PG8_WAIT_L(0); PG8_BAR; PG8_MMA(0, 0, At, B0); PG8_MMA(0, 1, At, B1); PG8_BAR; PG8_SCHED;
;             PG8_LDA(At, 1, 1); PG8_STAGE(PG8_SB(1, 0), b3, voffB); PG8_STAGE(PG8_SB(1, 1), b3 + hstep, voffB); PG8_STAGE(PG8_SA(1, 0), a3, voffA);
;             PG8_WAIT_V(8); PG8_WAIT_L(0); PG8_BAR; PG8_MMA(1, 0, At, B0); PG8_MMA(1, 1, At, B1); PG8_BAR; PG8_SCHED;
;         }
;         if constexpr (ALIGN_EPI) { if (wr == 0) PG8_BAR; }
;         const bool midseg = (NSEG == 2) && (cur.seg == 0);
;         if (midseg) E.mid(acc, cur, wr, wc, fr, fq); else if constexpr (!AFTER_DRAIN) E(acc, cur, wr, wc, fr, fq);
	v_mfma_f32_16x16x32_bf16 v[124:127], v[128:131], v[192:195], v[124:127]
	ds_read_b128 v[174:177], v162 offset:49152
	s_add_u32 s72, s72, 0x80
	s_addc_u32 s73, s73, 0
	v_mfma_f32_16x16x32_bf16 v[120:123], v[166:169], v[192:195], v[120:123]
	ds_read_b128 v[178:181], v162 offset:50176
	s_add_u32 s76, s76, 0x80
	s_addc_u32 s77, s77, 0
	v_mfma_f32_16x16x32_bf16 v[108:111], v[128:131], v[200:203], v[108:111]
	ds_read_b128 v[182:185], v162 offset:51200
	v_mfma_f32_16x16x32_bf16 v[104:107], v[166:169], v[200:203], v[104:107]
	ds_read_b128 v[188:191], v162 offset:52224
	v_mfma_f32_16x16x32_bf16 v[92:95], v[128:131], v[208:211], v[92:95]
	ds_read_b128 v[224:227], v164 offset:49152
	v_mfma_f32_16x16x32_bf16 v[88:91], v[166:169], v[208:211], v[88:91]
	ds_read_b128 v[228:231], v164 offset:50176
	v_mfma_f32_16x16x32_bf16 v[76:79], v[128:131], v[216:219], v[76:79]
	ds_read_b128 v[232:235], v164 offset:51200
	v_mfma_f32_16x16x32_bf16 v[72:75], v[166:169], v[216:219], v[72:75]
	ds_read_b128 v[236:239], v164 offset:52224
	v_mfma_f32_16x16x32_bf16 v[124:127], v[132:135], v[196:199], v[124:127]
	ds_read_b128 v[240:243], v164 offset:53248
	v_mfma_f32_16x16x32_bf16 v[120:123], v[170:173], v[196:199], v[120:123]
	ds_read_b128 v[244:247], v164 offset:54272
	v_mfma_f32_16x16x32_bf16 v[108:111], v[132:135], v[204:207], v[108:111]
	ds_read_b128 v[250:253], v164 offset:55296
	v_mfma_f32_16x16x32_bf16 v[104:107], v[170:173], v[204:207], v[104:107]
	ds_read_b128 v[150:153], v164 offset:56320
	v_mfma_f32_16x16x32_bf16 v[92:95], v[132:135], v[212:215], v[92:95]
	v_mfma_f32_16x16x32_bf16 v[88:91], v[170:173], v[212:215], v[88:91]
	v_mfma_f32_16x16x32_bf16 v[76:79], v[132:135], v[220:223], v[76:79]
	v_mfma_f32_16x16x32_bf16 v[72:75], v[170:173], v[220:223], v[72:75]
	s_waitcnt lgkmcnt(8)
	v_mfma_f32_16x16x32_bf16 v[116:119], v[174:177], v[192:195], v[116:119]
	v_mfma_f32_16x16x32_bf16 v[112:115], v[182:185], v[192:195], v[112:115]
	s_add_i32 m0, s33, 0x8000
	v_mfma_f32_16x16x32_bf16 v[100:103], v[174:177], v[200:203], v[100:103]
	global_load_lds_dwordx4 v138, s[72:73]
	v_mfma_f32_16x16x32_bf16 v[96:99], v[182:185], v[200:203], v[96:99]
	s_add_i32 m0, s33, 0xa000
	v_mfma_f32_16x16x32_bf16 v[84:87], v[174:177], v[208:211], v[84:87]
	global_load_lds_dwordx4 v142, s[72:73]
	v_mfma_f32_16x16x32_bf16 v[80:83], v[182:185], v[208:211], v[80:83]
	s_add_i32 m0, s33, 0x18000
	v_mfma_f32_16x16x32_bf16 v[68:71], v[174:177], v[216:219], v[68:71]
	global_load_lds_dwordx4 v140, s[76:77]
	v_mfma_f32_16x16x32_bf16 v[64:67], v[182:185], v[216:219], v[64:67]
	s_add_i32 m0, s33, 0x1a000
	v_mfma_f32_16x16x32_bf16 v[116:119], v[178:181], v[196:199], v[116:119]
	global_load_lds_dwordx4 v144, s[76:77]
	s_add_u32 s74, s74, 0x80
	s_addc_u32 s75, s75, 0
	v_mfma_f32_16x16x32_bf16 v[112:115], v[188:191], v[196:199], v[112:115]
	s_add_u32 s78, s78, 0x80
	s_addc_u32 s79, s79, 0
	v_mfma_f32_16x16x32_bf16 v[100:103], v[178:181], v[204:207], v[100:103]
	v_mfma_f32_16x16x32_bf16 v[96:99], v[188:191], v[204:207], v[96:99]
	v_mfma_f32_16x16x32_bf16 v[84:87], v[178:181], v[212:215], v[84:87]
	v_mfma_f32_16x16x32_bf16 v[80:83], v[188:191], v[212:215], v[80:83]
	v_mfma_f32_16x16x32_bf16 v[68:71], v[178:181], v[220:223], v[68:71]
	v_mfma_f32_16x16x32_bf16 v[64:67], v[188:191], v[220:223], v[64:67]
	s_waitcnt vmcnt(8) lgkmcnt(0)
	s_barrier
	v_mfma_f32_16x16x32_bf16 v[60:63], v[128:131], v[224:227], v[60:63]
	ds_read_b128 v[192:195], v164 offset:0
	v_mfma_f32_16x16x32_bf16 v[56:59], v[166:169], v[224:227], v[56:59]
	ds_read_b128 v[196:199], v164 offset:1024
	v_mfma_f32_16x16x32_bf16 v[44:47], v[128:131], v[232:235], v[44:47]
	ds_read_b128 v[200:203], v164 offset:2048
	v_mfma_f32_16x16x32_bf16 v[40:43], v[166:169], v[232:235], v[40:43]
	ds_read_b128 v[204:207], v164 offset:3072
	v_mfma_f32_16x16x32_bf16 v[28:31], v[128:131], v[240:243], v[28:31]
	ds_read_b128 v[208:211], v164 offset:4096
	v_mfma_f32_16x16x32_bf16 v[24:27], v[166:169], v[240:243], v[24:27]
	ds_read_b128 v[212:215], v164 offset:5120
	v_mfma_f32_16x16x32_bf16 v[12:15], v[128:131], v[250:253], v[12:15]
	ds_read_b128 v[216:219], v164 offset:6144
	v_mfma_f32_16x16x32_bf16 v[8:11], v[166:169], v[250:253], v[8:11]
	ds_read_b128 v[220:223], v164 offset:7168
	v_mfma_f32_16x16x32_bf16 v[60:63], v[132:135], v[228:231], v[60:63]
	v_mfma_f32_16x16x32_bf16 v[56:59], v[170:173], v[228:231], v[56:59]
	v_mfma_f32_16x16x32_bf16 v[44:47], v[132:135], v[236:239], v[44:47]
	v_mfma_f32_16x16x32_bf16 v[40:43], v[170:173], v[236:239], v[40:43]
	v_mfma_f32_16x16x32_bf16 v[28:31], v[132:135], v[244:247], v[28:31]
	v_mfma_f32_16x16x32_bf16 v[24:27], v[170:173], v[244:247], v[24:27]
	v_mfma_f32_16x16x32_bf16 v[12:15], v[132:135], v[150:153], v[12:15]
	v_mfma_f32_16x16x32_bf16 v[8:11], v[170:173], v[150:153], v[8:11]
	v_mfma_f32_16x16x32_bf16 v[52:55], v[174:177], v[224:227], v[52:55]
	v_mfma_f32_16x16x32_bf16 v[48:51], v[182:185], v[224:227], v[48:51]
	s_add_i32 m0, s33, 0xc000
	v_mfma_f32_16x16x32_bf16 v[36:39], v[174:177], v[232:235], v[36:39]
	global_load_lds_dwordx4 v138, s[74:75]
	v_mfma_f32_16x16x32_bf16 v[32:35], v[182:185], v[232:235], v[32:35]
	s_add_i32 m0, s33, 0xe000
	v_mfma_f32_16x16x32_bf16 v[20:23], v[174:177], v[240:243], v[20:23]
	global_load_lds_dwordx4 v142, s[74:75]
	v_mfma_f32_16x16x32_bf16 v[16:19], v[182:185], v[240:243], v[16:19]
	s_add_i32 m0, s33, 0x1c000
	v_mfma_f32_16x16x32_bf16 v[4:7], v[174:177], v[250:253], v[4:7]
	global_load_lds_dwordx4 v140, s[78:79]
	v_mfma_f32_16x16x32_bf16 v[0:3], v[182:185], v[250:253], v[0:3]
	s_add_i32 m0, s33, 0x1e000
	v_mfma_f32_16x16x32_bf16 v[52:55], v[178:181], v[228:231], v[52:55]
	global_load_lds_dwordx4 v144, s[78:79]
	v_mfma_f32_16x16x32_bf16 v[48:51], v[188:191], v[228:231], v[48:51]
	v_mfma_f32_16x16x32_bf16 v[36:39], v[178:181], v[236:239], v[36:39]
	ds_read_b128 v[128:131], v162 offset:0
	v_mfma_f32_16x16x32_bf16 v[32:35], v[188:191], v[236:239], v[32:35]
	ds_read_b128 v[132:135], v162 offset:1024
	s_add_u32 s72, s72, 0x80
	s_addc_u32 s73, s73, 0
	v_mfma_f32_16x16x32_bf16 v[20:23], v[178:181], v[244:247], v[20:23]
	ds_read_b128 v[166:169], v162 offset:2048
	s_add_u32 s76, s76, 0x80
	s_addc_u32 s77, s77, 0
	v_mfma_f32_16x16x32_bf16 v[16:19], v[188:191], v[244:247], v[16:19]
	ds_read_b128 v[170:173], v162 offset:3072
	s_add_i32 s80, s80, 1
	v_mfma_f32_16x16x32_bf16 v[4:7], v[178:181], v[150:153], v[4:7]
	v_mfma_f32_16x16x32_bf16 v[0:3], v[188:191], v[150:153], v[0:3]
	s_waitcnt vmcnt(8) lgkmcnt(0)
	s_barrier
	s_cmp_lt_u32 s80, 16
	s_cbranch_scc1 .Lp1_kloopB
	s_nop 7
.Lp1_exit:
	s_and_b64 vcc, exec, s[12:13]
	s_cbranch_vccz .LBB0_331
	s_cmp_gt_i32 s2, 31
	s_mov_b64 s[26:27], -1
	s_cbranch_scc1 .LBB0_332

; #define CONV2(W, A0, A1, A2, GW, wa, wb, wc_, j0) W = cvt_pk_bf16(bf_lo(GW) * (wa[j0] * bf_lo(A0) + wb[j0] * bf_lo(A1) + wc_[j0] * bf_lo(A2)), bf_hi(GW) * (wa[j0 + 1] * bf_hi(A0) + wb[j0 + 1] * bf_hi(A1) + wc_[j0 + 1] * bf_hi(A2)))
; __global__ void __launch_bounds__(NTHREADS, 2) fox_fwd(Args args) {
;     ...
;             int cur = (int)qslot[0];
;             while (cur < NCH) {
;                 __syncthreads();
;                 if (tid == 0) qslot[0] = __hip_atomic_fetch_add(qctr, 1u, __ATOMIC_RELAXED, __HIP_MEMORY_SCOPE_AGENT);
; #pragma unroll
;                 for (int i = 0; i < CH / 2; ++i) { const int row = cur * CH + rsub + 2 * i;
;                     const int b = row >> 12; const size_t pr = (size_t)(row + 2 * b) * DM + ch;
;                     const u32x4 a0 = *(const u32x4*)(P1b + pr), a1 = *(const u32x4*)(P1b + pr + DM), a2 = *(const u32x4*)(P1b + pr + 2 * DM), gg = *(const u32x4*)(P2b + (size_t)row * DM + ch);
;                     u32x4 o;
;                     CONV2(o.x, a0.x, a1.x, a2.x, gg.x, w0a, w1a, w2a, 0); CONV2(o.y, a0.y, a1.y, a2.y, gg.y, w0a, w1a, w2a, 2);
;                     CONV2(o.z, a0.z, a1.z, a2.z, gg.z, w0b, w1b, w2b, 0); CONV2(o.w, a0.w, a1.w, a2.w, gg.w, w0b, w1b, w2b, 2);
;                     *(u32x4*)(ACONV + (size_t)row * DM + ch) = o; }
.Lcv_body:
	v_lshl_or_b32 v16, v35, 3, v34
	v_ashrrev_i32_e32 v169, 11, v16
	v_and_b32_e32 v169, -2, v169
	v_add_u32_e32 v170, v169, v16
	v_ashrrev_i32_e32 v171, 31, v170
	v_ashrrev_i32_e32 v177, 31, v16
	v_mov_b32_e32 v176, v16
	v_lshlrev_b64 v[170:171], 12, v[170:171]
	v_lshlrev_b64 v[176:177], 12, v[176:177]
	v_lshl_add_u64 v[172:173], v[26:27], 0, v[170:171]
	v_lshl_add_u64 v[178:179], v[28:29], 0, v[176:177]
	v_add_co_u32_e32 v174, vcc, 0x2000, v172
	v_lshl_add_u64 v[160:161], v[30:31], 0, v[176:177]
	s_nop 0
	v_addc_co_u32_e32 v175, vcc, 0, v173, vcc
	global_load_dwordx4 v[96:99], v[172:173], off
	global_load_dwordx4 v[100:103], v[174:175], off offset:-4096
	global_load_dwordx4 v[104:107], v[178:179], off
	global_load_dwordx4 v[108:111], v[174:175], off
	v_add_u32_e32 v168, 2, v16
	v_ashrrev_i32_e32 v169, 11, v168
	v_and_b32_e32 v169, -2, v169
	v_add_u32_e32 v170, v169, v168
	v_ashrrev_i32_e32 v171, 31, v170
	v_ashrrev_i32_e32 v177, 31, v168
	v_mov_b32_e32 v176, v168
	v_lshlrev_b64 v[170:171], 12, v[170:171]
	v_lshlrev_b64 v[176:177], 12, v[176:177]
	v_lshl_add_u64 v[172:173], v[26:27], 0, v[170:171]
	v_lshl_add_u64 v[178:179], v[28:29], 0, v[176:177]
	v_add_co_u32_e32 v174, vcc, 0x2000, v172
	v_lshl_add_u64 v[162:163], v[30:31], 0, v[176:177]
	s_nop 0
	v_addc_co_u32_e32 v175, vcc, 0, v173, vcc
	global_load_dwordx4 v[112:115], v[172:173], off
	global_load_dwordx4 v[116:119], v[174:175], off offset:-4096
	global_load_dwordx4 v[120:123], v[178:179], off
	global_load_dwordx4 v[124:127], v[174:175], off
	v_add_u32_e32 v168, 4, v16
	v_ashrrev_i32_e32 v169, 11, v168
	v_and_b32_e32 v169, -2, v169
	v_add_u32_e32 v170, v169, v168
	v_ashrrev_i32_e32 v171, 31, v170
	v_ashrrev_i32_e32 v177, 31, v168
	v_mov_b32_e32 v176, v168
	v_lshlrev_b64 v[170:171], 12, v[170:171]
	v_lshlrev_b64 v[176:177], 12, v[176:177]
	v_lshl_add_u64 v[172:173], v[26:27], 0, v[170:171]
	v_lshl_add_u64 v[178:179], v[28:29], 0, v[176:177]
	v_add_co_u32_e32 v174, vcc, 0x2000, v172
	v_lshl_add_u64 v[164:165], v[30:31], 0, v[176:177]
	s_nop 0
	v_addc_co_u32_e32 v175, vcc, 0, v173, vcc
	global_load_dwordx4 v[128:131], v[172:173], off
	global_load_dwordx4 v[132:135], v[174:175], off offset:-4096
	global_load_dwordx4 v[136:139], v[178:179], off
	global_load_dwordx4 v[140:143], v[174:175], off
	v_add_u32_e32 v168, 6, v16
	v_ashrrev_i32_e32 v169, 11, v168
	v_and_b32_e32 v169, -2, v169
	v_add_u32_e32 v170, v169, v168
	v_ashrrev_i32_e32 v171, 31, v170
	v_ashrrev_i32_e32 v177, 31, v168
	v_mov_b32_e32 v176, v168
	v_lshlrev_b64 v[170:171], 12, v[170:171]
	v_lshlrev_b64 v[176:177], 12, v[176:177]
	v_lshl_add_u64 v[172:173], v[26:27], 0, v[170:171]
	v_lshl_add_u64 v[178:179], v[28:29], 0, v[176:177]
	v_add_co_u32_e32 v174, vcc, 0x2000, v172
	v_lshl_add_u64 v[166:167], v[30:31], 0, v[176:177]
	s_nop 0
	v_addc_co_u32_e32 v175, vcc, 0, v173, vcc
	global_load_dwordx4 v[144:147], v[172:173], off
	global_load_dwordx4 v[148:151], v[174:175], off offset:-4096
	global_load_dwordx4 v[152:155], v[178:179], off
	global_load_dwordx4 v[156:159], v[174:175], off
	s_waitcnt vmcnt(12)
	s_and_saveexec_b64 s[4:5], s[0:1]
	s_cbranch_execz .Lcv_nocons
	v_readfirstlane_b32 s6, v84
	v_mov_b32_e32 v85, s10
	s_nop 1
	v_add_u32_e32 v83, s6, v83
	ds_write_b32 v85, v83
.Lcv_nocons:
	s_or_b64 exec, exec, s[4:5]
	v_mov_b32_e32 v36, v96
	v_mov_b32_e32 v37, v97
	v_mov_b32_e32 v38, v98
	v_mov_b32_e32 v39, v99
	v_mov_b32_e32 v40, v100
	v_mov_b32_e32 v41, v101
	v_mov_b32_e32 v42, v102
	v_mov_b32_e32 v43, v103
	v_mov_b32_e32 v44, v104
	v_mov_b32_e32 v45, v105
	v_mov_b32_e32 v46, v106
	v_mov_b32_e32 v47, v107
	v_mov_b32_e32 v48, v108
	v_mov_b32_e32 v49, v109
	v_mov_b32_e32 v50, v110
	v_mov_b32_e32 v51, v111
	v_mov_b32_e32 v52, v160
	v_mov_b32_e32 v53, v161
	v_lshlrev_b32_e32 v56, 16, v36
	v_and_b32_e32 v36, 0xffff0000, v36
	v_lshlrev_b32_e32 v58, 16, v37
	v_and_b32_e32 v60, 0xffff0000, v37
	v_and_b32_e32 v37, 0xffff0000, v48
	v_lshlrev_b32_e32 v62, 16, v38
	v_and_b32_e32 v38, 0xffff0000, v38
	v_lshlrev_b32_e32 v64, 16, v39
	v_and_b32_e32 v66, 0xffff0000, v39
	v_and_b32_e32 v68, 0xffff0000, v40
	v_lshlrev_b32_e32 v57, 16, v48
	v_lshlrev_b32_e32 v59, 16, v49
	v_and_b32_e32 v39, 0xffff0000, v50
	v_lshlrev_b32_e32 v65, 16, v51
	v_pk_mul_f32 v[36:37], v[4:5], v[36:37]
	v_lshlrev_b32_e32 v55, 16, v40
	v_lshlrev_b32_e32 v69, 16, v41
	v_and_b32_e32 v70, 0xffff0000, v41
	v_lshlrev_b32_e32 v71, 16, v42
	v_and_b32_e32 v72, 0xffff0000, v42
	v_lshlrev_b32_e32 v73, 16, v43
	v_and_b32_e32 v74, 0xffff0000, v43
	v_and_b32_e32 v61, 0xffff0000, v49
	v_lshlrev_b32_e32 v63, 16, v50
	v_and_b32_e32 v67, 0xffff0000, v51
	v_pk_mul_f32 v[40:41], v[18:19], v[56:57]
	v_pk_mul_f32 v[42:43], v[20:21], v[58:59]
	v_pk_mul_f32 v[38:39], v[12:13], v[38:39]
	v_pk_mul_f32 v[48:49], v[32:33], v[64:65]
	v_fma_f32 v36, v1, v68, v36
	v_lshlrev_b32_e32 v75, 16, v44
	v_and_b32_e32 v76, 0xffff0000, v44
	v_lshlrev_b32_e32 v77, 16, v45
	v_and_b32_e32 v78, 0xffff0000, v45
	v_lshlrev_b32_e32 v79, 16, v46
	v_and_b32_e32 v80, 0xffff0000, v46
	v_lshlrev_b32_e32 v81, 16, v47
	v_and_b32_e32 v82, 0xffff0000, v47
	v_pk_mul_f32 v[44:45], v[6:7], v[60:61]
	v_pk_mul_f32 v[46:47], v[22:23], v[62:63]
	v_pk_mul_f32 v[50:51], v[14:15], v[66:67]
	v_fma_f32 v40, v0, v55, v40
	v_fma_f32 v42, v2, v69, v42
	v_fma_f32 v38, v9, v72, v38
	v_fma_f32 v48, v10, v73, v48
	v_add_f32_e32 v36, v36, v37
	v_fma_f32 v44, v3, v70, v44
	v_fma_f32 v46, v8, v71, v46
	v_fma_f32 v50, v11, v74, v50
	v_add_f32_e32 v40, v40, v41
	v_add_f32_e32 v37, v42, v43
	v_add_f32_e32 v38, v38, v39
	v_add_f32_e32 v39, v48, v49
	v_mul_f32_e32 v36, v36, v76
	v_add_f32_e32 v41, v44, v45
	v_add_f32_e32 v42, v46, v47
	v_add_f32_e32 v43, v50, v51
	v_mul_f32_e32 v40, v40, v75
	v_mul_f32_e32 v37, v37, v77
	v_mul_f32_e32 v38, v38, v80
	v_mul_f32_e32 v39, v39, v81
	v_cvt_pk_bf16_f32 v36, v40, v36
	v_mul_f32_e32 v41, v41, v78
	v_mul_f32_e32 v42, v42, v79
	v_mul_f32_e32 v43, v43, v82
	v_cvt_pk_bf16_f32 v37, v37, v41
	v_cvt_pk_bf16_f32 v38, v42, v38
	v_cvt_pk_bf16_f32 v39, v39, v43
	global_store_dwordx4 v[52:53], v[36:39], off
	s_nop 1
	s_waitcnt vmcnt(9)
; #define CONV2(W, A0, A1, A2, GW, wa, wb, wc_, j0) W = cvt_pk_bf16(bf_lo(GW) * (wa[j0] * bf_lo(A0) + wb[j0] * bf_lo(A1) + wc_[j0] * bf_lo(A2)), bf_hi(GW) * (wa[j0 + 1] * bf_hi(A0) + wb[j0 + 1] * bf_hi(A1) + wc_[j0 + 1] * bf_hi(A2)))
; __global__ void __launch_bounds__(NTHREADS, 2) fox_fwd(Args args) {
;     ...
;                 for (int i = 0; i < CH / 2; ++i) { const int row = cur * CH + rsub + 2 * i;
;                     const int b = row >> 12; const size_t pr = (size_t)(row + 2 * b) * DM + ch;
;                     const u32x4 a0 = *(const u32x4*)(P1b + pr), a1 = *(const u32x4*)(P1b + pr + DM), a2 = *(const u32x4*)(P1b + pr + 2 * DM), gg = *(const u32x4*)(P2b + (size_t)row * DM + ch);
;                     u32x4 o;
;                     CONV2(o.x, a0.x, a1.x, a2.x, gg.x, w0a, w1a, w2a, 0); CONV2(o.y, a0.y, a1.y, a2.y, gg.y, w0a, w1a, w2a, 2);
;                     CONV2(o.z, a0.z, a1.z, a2.z, gg.z, w0b, w1b, w2b, 0); CONV2(o.w, a0.w, a1.w, a2.w, gg.w, w0b, w1b, w2b, 2);
;                     *(u32x4*)(ACONV + (size_t)row * DM + ch) = o; }
	v_mov_b32_e32 v36, v112
	v_mov_b32_e32 v37, v113
	v_mov_b32_e32 v38, v114
	v_mov_b32_e32 v39, v115
	v_mov_b32_e32 v40, v116
	v_mov_b32_e32 v41, v117
	v_mov_b32_e32 v42, v118
	v_mov_b32_e32 v43, v119
	v_mov_b32_e32 v44, v120
	v_mov_b32_e32 v45, v121
	v_mov_b32_e32 v46, v122
	v_mov_b32_e32 v47, v123
	v_mov_b32_e32 v48, v124
	v_mov_b32_e32 v49, v125
	v_mov_b32_e32 v50, v126
	v_mov_b32_e32 v51, v127
	v_mov_b32_e32 v52, v162
	v_mov_b32_e32 v53, v163
	v_lshlrev_b32_e32 v56, 16, v36
	v_and_b32_e32 v36, 0xffff0000, v36
	v_lshlrev_b32_e32 v58, 16, v37
	v_and_b32_e32 v60, 0xffff0000, v37
	v_and_b32_e32 v37, 0xffff0000, v48
	v_lshlrev_b32_e32 v62, 16, v38
	v_and_b32_e32 v38, 0xffff0000, v38
	v_lshlrev_b32_e32 v64, 16, v39
	v_and_b32_e32 v66, 0xffff0000, v39
	v_and_b32_e32 v68, 0xffff0000, v40
	v_lshlrev_b32_e32 v57, 16, v48
	v_lshlrev_b32_e32 v59, 16, v49
	v_and_b32_e32 v39, 0xffff0000, v50
	v_lshlrev_b32_e32 v65, 16, v51
	v_pk_mul_f32 v[36:37], v[4:5], v[36:37]
	v_lshlrev_b32_e32 v55, 16, v40
	v_lshlrev_b32_e32 v69, 16, v41
	v_and_b32_e32 v70, 0xffff0000, v41
	v_lshlrev_b32_e32 v71, 16, v42
	v_and_b32_e32 v72, 0xffff0000, v42
	v_lshlrev_b32_e32 v73, 16, v43
	v_and_b32_e32 v74, 0xffff0000, v43
	v_and_b32_e32 v61, 0xffff0000, v49
	v_lshlrev_b32_e32 v63, 16, v50
	v_and_b32_e32 v67, 0xffff0000, v51
	v_pk_mul_f32 v[40:41], v[18:19], v[56:57]
	v_pk_mul_f32 v[42:43], v[20:21], v[58:59]
	v_pk_mul_f32 v[38:39], v[12:13], v[38:39]
	v_pk_mul_f32 v[48:49], v[32:33], v[64:65]
	v_fma_f32 v36, v1, v68, v36
	v_lshlrev_b32_e32 v75, 16, v44
	v_and_b32_e32 v76, 0xffff0000, v44
	v_lshlrev_b32_e32 v77, 16, v45
	v_and_b32_e32 v78, 0xffff0000, v45
	v_lshlrev_b32_e32 v79, 16, v46
	v_and_b32_e32 v80, 0xffff0000, v46
	v_lshlrev_b32_e32 v81, 16, v47
	v_and_b32_e32 v82, 0xffff0000, v47
	v_pk_mul_f32 v[44:45], v[6:7], v[60:61]
	v_pk_mul_f32 v[46:47], v[22:23], v[62:63]
	v_pk_mul_f32 v[50:51], v[14:15], v[66:67]
	v_fma_f32 v40, v0, v55, v40
	v_fma_f32 v42, v2, v69, v42
	v_fma_f32 v38, v9, v72, v38
	v_fma_f32 v48, v10, v73, v48
	v_add_f32_e32 v36, v36, v37
	v_fma_f32 v44, v3, v70, v44
	v_fma_f32 v46, v8, v71, v46
	v_fma_f32 v50, v11, v74, v50
	v_add_f32_e32 v40, v40, v41
	v_add_f32_e32 v37, v42, v43
	v_add_f32_e32 v38, v38, v39
	v_add_f32_e32 v39, v48, v49
	v_mul_f32_e32 v36, v36, v76
	v_add_f32_e32 v41, v44, v45
	v_add_f32_e32 v42, v46, v47
	v_add_f32_e32 v43, v50, v51
	v_mul_f32_e32 v40, v40, v75
	v_mul_f32_e32 v37, v37, v77
	v_mul_f32_e32 v38, v38, v80
	v_mul_f32_e32 v39, v39, v81
	v_cvt_pk_bf16_f32 v36, v40, v36
	v_mul_f32_e32 v41, v41, v78
	v_mul_f32_e32 v42, v42, v79
	v_mul_f32_e32 v43, v43, v82
	v_cvt_pk_bf16_f32 v37, v37, v41
	v_cvt_pk_bf16_f32 v38, v42, v38
	v_cvt_pk_bf16_f32 v39, v39, v43
	global_store_dwordx4 v[52:53], v[36:39], off
	s_nop 1
	s_waitcnt vmcnt(6)
	v_mov_b32_e32 v36, v128
	v_mov_b32_e32 v37, v129
	v_mov_b32_e32 v38, v130
	v_mov_b32_e32 v39, v131
	v_mov_b32_e32 v40, v132
	v_mov_b32_e32 v41, v133
	v_mov_b32_e32 v42, v134
	v_mov_b32_e32 v43, v135
	v_mov_b32_e32 v44, v136
	v_mov_b32_e32 v45, v137
	v_mov_b32_e32 v46, v138
	v_mov_b32_e32 v47, v139
	v_mov_b32_e32 v48, v140
	v_mov_b32_e32 v49, v141
	v_mov_b32_e32 v50, v142
	v_mov_b32_e32 v51, v143
	v_mov_b32_e32 v52, v164
	v_mov_b32_e32 v53, v165
	v_lshlrev_b32_e32 v56, 16, v36
	v_and_b32_e32 v36, 0xffff0000, v36
	v_lshlrev_b32_e32 v58, 16, v37
	v_and_b32_e32 v60, 0xffff0000, v37
	v_and_b32_e32 v37, 0xffff0000, v48
	v_lshlrev_b32_e32 v62, 16, v38
	v_and_b32_e32 v38, 0xffff0000, v38
	v_lshlrev_b32_e32 v64, 16, v39
	v_and_b32_e32 v66, 0xffff0000, v39
	v_and_b32_e32 v68, 0xffff0000, v40
	v_lshlrev_b32_e32 v57, 16, v48
	v_lshlrev_b32_e32 v59, 16, v49
	v_and_b32_e32 v39, 0xffff0000, v50
	v_lshlrev_b32_e32 v65, 16, v51
	v_pk_mul_f32 v[36:37], v[4:5], v[36:37]
	v_lshlrev_b32_e32 v55, 16, v40
	v_lshlrev_b32_e32 v69, 16, v41
	v_and_b32_e32 v70, 0xffff0000, v41
	v_lshlrev_b32_e32 v71, 16, v42
	v_and_b32_e32 v72, 0xffff0000, v42
	v_lshlrev_b32_e32 v73, 16, v43
	v_and_b32_e32 v74, 0xffff0000, v43
	v_and_b32_e32 v61, 0xffff0000, v49
	v_lshlrev_b32_e32 v63, 16, v50
	v_and_b32_e32 v67, 0xffff0000, v51
	v_pk_mul_f32 v[40:41], v[18:19], v[56:57]
	v_pk_mul_f32 v[42:43], v[20:21], v[58:59]
	v_pk_mul_f32 v[38:39], v[12:13], v[38:39]
	v_pk_mul_f32 v[48:49], v[32:33], v[64:65]
	v_fma_f32 v36, v1, v68, v36
	v_lshlrev_b32_e32 v75, 16, v44
	v_and_b32_e32 v76, 0xffff0000, v44
	v_lshlrev_b32_e32 v77, 16, v45
	v_and_b32_e32 v78, 0xffff0000, v45
	v_lshlrev_b32_e32 v79, 16, v46
	v_and_b32_e32 v80, 0xffff0000, v46
	v_lshlrev_b32_e32 v81, 16, v47
	v_and_b32_e32 v82, 0xffff0000, v47
	v_pk_mul_f32 v[44:45], v[6:7], v[60:61]
	v_pk_mul_f32 v[46:47], v[22:23], v[62:63]
	v_pk_mul_f32 v[50:51], v[14:15], v[66:67]
	v_fma_f32 v40, v0, v55, v40
	v_fma_f32 v42, v2, v69, v42
	v_fma_f32 v38, v9, v72, v38
	v_fma_f32 v48, v10, v73, v48
	v_add_f32_e32 v36, v36, v37
	v_fma_f32 v44, v3, v70, v44
	v_fma_f32 v46, v8, v71, v46
	v_fma_f32 v50, v11, v74, v50
	v_add_f32_e32 v40, v40, v41
	v_add_f32_e32 v37, v42, v43
	v_add_f32_e32 v38, v38, v39
	v_add_f32_e32 v39, v48, v49
	v_mul_f32_e32 v36, v36, v76
	v_add_f32_e32 v41, v44, v45
	v_add_f32_e32 v42, v46, v47
	v_add_f32_e32 v43, v50, v51
	v_mul_f32_e32 v40, v40, v75
	v_mul_f32_e32 v37, v37, v77
	v_mul_f32_e32 v38, v38, v80
	v_mul_f32_e32 v39, v39, v81
	v_cvt_pk_bf16_f32 v36, v40, v36
	v_mul_f32_e32 v41, v41, v78
	v_mul_f32_e32 v42, v42, v79
	v_mul_f32_e32 v43, v43, v82
	v_cvt_pk_bf16_f32 v37, v37, v41
	v_cvt_pk_bf16_f32 v38, v42, v38
	v_cvt_pk_bf16_f32 v39, v39, v43
	global_store_dwordx4 v[52:53], v[36:39], off
	s_nop 1
	s_waitcnt vmcnt(3)
; #define CONV2(W, A0, A1, A2, GW, wa, wb, wc_, j0) W = cvt_pk_bf16(bf_lo(GW) * (wa[j0] * bf_lo(A0) + wb[j0] * bf_lo(A1) + wc_[j0] * bf_lo(A2)), bf_hi(GW) * (wa[j0 + 1] * bf_hi(A0) + wb[j0 + 1] * bf_hi(A1) + wc_[j0 + 1] * bf_hi(A2)))
; __global__ void __launch_bounds__(NTHREADS, 2) fox_fwd(Args args) {
;     ...
;             while (cur < NCH) {
;                 __syncthreads();
;                 if (tid == 0) qslot[0] = __hip_atomic_fetch_add(qctr, 1u, __ATOMIC_RELAXED, __HIP_MEMORY_SCOPE_AGENT);
; #pragma unroll
;                 for (int i = 0; i < CH / 2; ++i) { const int row = cur * CH + rsub + 2 * i;
;                     const int b = row >> 12; const size_t pr = (size_t)(row + 2 * b) * DM + ch;
;                     const u32x4 a0 = *(const u32x4*)(P1b + pr), a1 = *(const u32x4*)(P1b + pr + DM), a2 = *(const u32x4*)(P1b + pr + 2 * DM), gg = *(const u32x4*)(P2b + (size_t)row * DM + ch);
;                     u32x4 o;
;                     CONV2(o.x, a0.x, a1.x, a2.x, gg.x, w0a, w1a, w2a, 0); CONV2(o.y, a0.y, a1.y, a2.y, gg.y, w0a, w1a, w2a, 2);
;                     CONV2(o.z, a0.z, a1.z, a2.z, gg.z, w0b, w1b, w2b, 0); CONV2(o.w, a0.w, a1.w, a2.w, gg.w, w0b, w1b, w2b, 2);
;                     *(u32x4*)(ACONV + (size_t)row * DM + ch) = o; }
;                 __syncthreads();
;                 cur = (int)qslot[0];
;             }
	v_mov_b32_e32 v36, v144
	v_mov_b32_e32 v37, v145
	v_mov_b32_e32 v38, v146
	v_mov_b32_e32 v39, v147
	v_mov_b32_e32 v40, v148
	v_mov_b32_e32 v41, v149
	v_mov_b32_e32 v42, v150
	v_mov_b32_e32 v43, v151
	v_mov_b32_e32 v44, v152
	v_mov_b32_e32 v45, v153
	v_mov_b32_e32 v46, v154
	v_mov_b32_e32 v47, v155
	v_mov_b32_e32 v48, v156
	v_mov_b32_e32 v49, v157
	v_mov_b32_e32 v50, v158
	v_mov_b32_e32 v51, v159
	v_mov_b32_e32 v52, v166
	v_mov_b32_e32 v53, v167
	v_lshlrev_b32_e32 v56, 16, v36
	v_and_b32_e32 v36, 0xffff0000, v36
	v_lshlrev_b32_e32 v58, 16, v37
	v_and_b32_e32 v60, 0xffff0000, v37
	v_and_b32_e32 v37, 0xffff0000, v48
	v_lshlrev_b32_e32 v62, 16, v38
	v_and_b32_e32 v38, 0xffff0000, v38
	v_lshlrev_b32_e32 v64, 16, v39
	v_and_b32_e32 v66, 0xffff0000, v39
	v_and_b32_e32 v68, 0xffff0000, v40
	v_lshlrev_b32_e32 v57, 16, v48
	v_lshlrev_b32_e32 v59, 16, v49
	v_and_b32_e32 v39, 0xffff0000, v50
	v_lshlrev_b32_e32 v65, 16, v51
	v_pk_mul_f32 v[36:37], v[4:5], v[36:37]
	v_lshlrev_b32_e32 v55, 16, v40
	v_lshlrev_b32_e32 v69, 16, v41
	v_and_b32_e32 v70, 0xffff0000, v41
	v_lshlrev_b32_e32 v71, 16, v42
	v_and_b32_e32 v72, 0xffff0000, v42
	v_lshlrev_b32_e32 v73, 16, v43
	v_and_b32_e32 v74, 0xffff0000, v43
	v_and_b32_e32 v61, 0xffff0000, v49
	v_lshlrev_b32_e32 v63, 16, v50
	v_and_b32_e32 v67, 0xffff0000, v51
	v_pk_mul_f32 v[40:41], v[18:19], v[56:57]
	v_pk_mul_f32 v[42:43], v[20:21], v[58:59]
	v_pk_mul_f32 v[38:39], v[12:13], v[38:39]
	v_pk_mul_f32 v[48:49], v[32:33], v[64:65]
	v_fma_f32 v36, v1, v68, v36
	v_lshlrev_b32_e32 v75, 16, v44
	v_and_b32_e32 v76, 0xffff0000, v44
	v_lshlrev_b32_e32 v77, 16, v45
	v_and_b32_e32 v78, 0xffff0000, v45
	v_lshlrev_b32_e32 v79, 16, v46
	v_and_b32_e32 v80, 0xffff0000, v46
	v_lshlrev_b32_e32 v81, 16, v47
	v_and_b32_e32 v82, 0xffff0000, v47
	v_pk_mul_f32 v[44:45], v[6:7], v[60:61]
	v_pk_mul_f32 v[46:47], v[22:23], v[62:63]
	v_pk_mul_f32 v[50:51], v[14:15], v[66:67]
	v_fma_f32 v40, v0, v55, v40
	v_fma_f32 v42, v2, v69, v42
	v_fma_f32 v38, v9, v72, v38
	v_fma_f32 v48, v10, v73, v48
	v_add_f32_e32 v36, v36, v37
	v_fma_f32 v44, v3, v70, v44
	v_fma_f32 v46, v8, v71, v46
	v_fma_f32 v50, v11, v74, v50
	v_add_f32_e32 v40, v40, v41
	v_add_f32_e32 v37, v42, v43
	v_add_f32_e32 v38, v38, v39
	v_add_f32_e32 v39, v48, v49
	v_mul_f32_e32 v36, v36, v76
	v_add_f32_e32 v41, v44, v45
	v_add_f32_e32 v42, v46, v47
	v_add_f32_e32 v43, v50, v51
	v_mul_f32_e32 v40, v40, v75
	v_mul_f32_e32 v37, v37, v77
	v_mul_f32_e32 v38, v38, v80
	v_mul_f32_e32 v39, v39, v81
	v_cvt_pk_bf16_f32 v36, v40, v36
	v_mul_f32_e32 v41, v41, v78
	v_mul_f32_e32 v42, v42, v79
	v_mul_f32_e32 v43, v43, v82
	v_cvt_pk_bf16_f32 v37, v37, v41
	v_cvt_pk_bf16_f32 v38, v42, v38
	v_cvt_pk_bf16_f32 v39, v39, v43
	global_store_dwordx4 v[52:53], v[36:39], off
	s_nop 1
	s_waitcnt lgkmcnt(0)
	s_barrier
	ds_read_b32 v35, v24
	s_waitcnt lgkmcnt(0)
	v_cmp_gt_i32_e32 vcc, s12, v35
	s_cbranch_vccz .LBB0_601
.LBB0_598:
	s_barrier
	s_and_saveexec_b64 s[4:5], s[0:1]
	s_cbranch_execz .Lcv_noatom
	s_mov_b64 s[8:9], exec
	v_mbcnt_lo_u32_b32 v83, s8, 0
	v_mbcnt_hi_u32_b32 v83, s9, v83
	v_cmp_eq_u32_e32 vcc, 0, v83
	s_and_saveexec_b64 s[6:7], vcc
	s_cbranch_execz .Lcv_a1
	s_bcnt1_i32_b64 s8, s[8:9]
	v_mov_b32_e32 v84, s8
	global_atomic_add v84, v25, v84, s[2:3] sc0

; __global__ void __launch_bounds__(NTHREADS, 2) fox_fwd(Args args) {
;     ...
;             while (cur < NCH) {
;                 __syncthreads();
;                 if (tid == 0) qslot[0] = __hip_atomic_fetch_add(qctr, 1u, __ATOMIC_RELAXED, __HIP_MEMORY_SCOPE_AGENT);
.Lcv_noatom:
	s_or_b64 exec, exec, s[4:5]
	s_branch .Lcv_body

; __global__ void __launch_bounds__(NTHREADS, 2) fox_fwd(Args args) {
	.amdhsa_kernel _Z7fox_fwd4Args
		.amdhsa_group_segment_fixed_size 0
		.amdhsa_private_segment_fixed_size 0
		.amdhsa_kernarg_size 360
		.amdhsa_user_sgpr_count 2
		.amdhsa_user_sgpr_dispatch_ptr 0
		.amdhsa_user_sgpr_queue_ptr 0
		.amdhsa_user_sgpr_kernarg_segment_ptr 1
		.amdhsa_user_sgpr_dispatch_id 0
		.amdhsa_user_sgpr_kernarg_preload_length 0
		.amdhsa_user_sgpr_kernarg_preload_offset 0
		.amdhsa_user_sgpr_private_segment_size 0
		.amdhsa_uses_dynamic_stack 0
		.amdhsa_enable_private_segment 0
		.amdhsa_system_sgpr_workgroup_id_x 1
		.amdhsa_system_sgpr_workgroup_id_y 0
		.amdhsa_system_sgpr_workgroup_id_z 0
		.amdhsa_system_sgpr_workgroup_info 0
		.amdhsa_system_vgpr_workitem_id 2
		.amdhsa_next_free_vgpr 254
		.amdhsa_next_free_sgpr 102
		.amdhsa_accum_offset 256
		.amdhsa_reserve_vcc 1
		.amdhsa_float_round_mode_32 0
		.amdhsa_float_round_mode_16_64 0
		.amdhsa_float_denorm_mode_32 3
		.amdhsa_float_denorm_mode_16_64 3
		.amdhsa_dx10_clamp 1
		.amdhsa_ieee_mode 1
		.amdhsa_fp16_overflow 0
		.amdhsa_tg_split 0
		.amdhsa_exception_fp_ieee_invalid_op 0
		.amdhsa_exception_fp_denorm_src 0
		.amdhsa_exception_fp_ieee_div_zero 0
		.amdhsa_exception_fp_ieee_overflow 0
		.amdhsa_exception_fp_ieee_underflow 0
		.amdhsa_exception_fp_ieee_inexact 0
		.amdhsa_exception_int_div_zero 0
	.end_amdhsa_kernel
